# K-loops: fragment reads issued in MFMA consumption order with per-fragment counted waits
# baseline (speedup 1.0000x reference)
.LBB0_243:
	s_cmpk_eq_i32 s4, 0x700
	v_lshl_add_u64 v[170:171], v[152:153], 0, s[4:5]
	s_mov_b64 s[6:7], 0x4280100
	v_lshl_add_u64 v[170:171], v[170:171], 0, s[6:7]
	s_cselect_b64 vcc, -1, 0
	s_add_i32 s6, 0, 0x10000
	v_cndmask_b32_e32 v245, v171, v147, vcc
	v_add_u32_e32 v171, s6, v174
	ds_read_b128 v[176:179], v171
	ds_read_b128 v[184:187], v171 offset:2048
	ds_read_b128 v[180:183], v171 offset:1024
	ds_read_b128 v[188:191], v171 offset:3072
	v_cndmask_b32_e32 v244, v170, v146, vcc
	v_lshl_add_u64 v[170:171], v[168:169], 0, s[4:5]
	v_cndmask_b32_e32 v171, v171, v145, vcc
	v_cndmask_b32_e32 v170, v170, v144, vcc
	v_lshl_add_u64 v[228:229], v[148:149], 0, s[4:5]
	s_add_i32 m0, s26, 0xc000
	ds_read_b128 v[192:195], v175
	ds_read_b128 v[200:203], v175 offset:2048
	ds_read_b128 v[210:213], v175 offset:4096
	ds_read_b128 v[218:221], v175 offset:6144
	ds_read_b128 v[196:199], v175 offset:1024
	ds_read_b128 v[204:207], v175 offset:3072
	ds_read_b128 v[214:217], v175 offset:5120
	ds_read_b128 v[222:225], v175 offset:7168
	global_load_lds_dwordx4 v[228:229], off
	v_lshl_add_u64 v[228:229], v[150:151], 0, s[4:5]
	s_add_i32 m0, s26, 0xe000
	s_nop 0
	global_load_lds_dwordx4 v[228:229], off
	s_waitcnt lgkmcnt(8)
	s_barrier
	s_setprio 1
	s_waitcnt lgkmcnt(7)
	v_mfma_f32_16x16x32_bf16 v[126:129], v[176:179], v[192:195], v[126:129]
	v_mfma_f32_16x16x32_bf16 v[122:125], v[184:187], v[192:195], v[122:125]
	s_waitcnt lgkmcnt(6)
	v_mfma_f32_16x16x32_bf16 v[118:121], v[176:179], v[200:203], v[118:121]
	v_mfma_f32_16x16x32_bf16 v[114:117], v[184:187], v[200:203], v[114:117]
	s_waitcnt lgkmcnt(5)
	v_mfma_f32_16x16x32_bf16 v[110:113], v[176:179], v[210:213], v[110:113]
	v_mfma_f32_16x16x32_bf16 v[106:109], v[184:187], v[210:213], v[106:109]
	s_waitcnt lgkmcnt(4)
	v_mfma_f32_16x16x32_bf16 v[102:105], v[176:179], v[218:221], v[102:105]
	v_mfma_f32_16x16x32_bf16 v[98:101], v[184:187], v[218:221], v[98:101]
	s_waitcnt lgkmcnt(3)
	v_mfma_f32_16x16x32_bf16 v[126:129], v[180:183], v[196:199], v[126:129]
	v_mfma_f32_16x16x32_bf16 v[122:125], v[188:191], v[196:199], v[122:125]
	s_waitcnt lgkmcnt(2)
	v_mfma_f32_16x16x32_bf16 v[118:121], v[180:183], v[204:207], v[118:121]
	v_mfma_f32_16x16x32_bf16 v[114:117], v[188:191], v[204:207], v[114:117]
	s_waitcnt lgkmcnt(1)
	v_mfma_f32_16x16x32_bf16 v[110:113], v[180:183], v[214:217], v[110:113]
	v_mfma_f32_16x16x32_bf16 v[106:109], v[188:191], v[214:217], v[106:109]
	s_waitcnt lgkmcnt(0)
	v_mfma_f32_16x16x32_bf16 v[102:105], v[180:183], v[222:225], v[102:105]
	v_mfma_f32_16x16x32_bf16 v[98:101], v[188:191], v[222:225], v[98:101]
	s_setprio 0
	s_barrier
	s_add_i32 s7, 0, 0x14000
	s_add_i32 s6, s6, s13
	v_add_u32_e32 v208, s7, v174
	v_lshl_add_u64 v[246:247], v[170:171], 0, v[132:133]
	s_mov_b32 m0, s6
	ds_read_b128 v[228:231], v208
	ds_read_b128 v[236:239], v208 offset:2048
	ds_read_b128 v[232:235], v208 offset:1024
	ds_read_b128 v[240:243], v208 offset:3072
	global_load_lds_dwordx4 v[246:247], off
	v_lshl_add_u64 v[248:249], v[170:171], 0, v[142:143]
	s_add_i32 m0, s6, 0x2000
	s_nop 0
	global_load_lds_dwordx4 v[248:249], off
	s_barrier
	s_setprio 1
	s_waitcnt lgkmcnt(3)
	v_mfma_f32_16x16x32_bf16 v[94:97], v[228:231], v[192:195], v[94:97]
	s_waitcnt lgkmcnt(2)
	v_mfma_f32_16x16x32_bf16 v[90:93], v[236:239], v[192:195], v[90:93]
	v_mfma_f32_16x16x32_bf16 v[86:89], v[228:231], v[200:203], v[86:89]
	v_mfma_f32_16x16x32_bf16 v[82:85], v[236:239], v[200:203], v[82:85]
	v_mfma_f32_16x16x32_bf16 v[78:81], v[228:231], v[210:213], v[78:81]
	v_mfma_f32_16x16x32_bf16 v[74:77], v[236:239], v[210:213], v[74:77]
	v_mfma_f32_16x16x32_bf16 v[70:73], v[228:231], v[218:221], v[70:73]
	v_mfma_f32_16x16x32_bf16 v[66:69], v[236:239], v[218:221], v[66:69]
	s_waitcnt lgkmcnt(1)
	v_mfma_f32_16x16x32_bf16 v[94:97], v[232:235], v[196:199], v[94:97]
	s_waitcnt lgkmcnt(0)
	v_mfma_f32_16x16x32_bf16 v[90:93], v[240:243], v[196:199], v[90:93]
	v_mfma_f32_16x16x32_bf16 v[86:89], v[232:235], v[204:207], v[86:89]
	v_mfma_f32_16x16x32_bf16 v[82:85], v[240:243], v[204:207], v[82:85]
	v_mfma_f32_16x16x32_bf16 v[78:81], v[232:235], v[214:217], v[78:81]
	v_mfma_f32_16x16x32_bf16 v[74:77], v[240:243], v[214:217], v[74:77]
	v_mfma_f32_16x16x32_bf16 v[70:73], v[232:235], v[222:225], v[70:73]
	v_mfma_f32_16x16x32_bf16 v[66:69], v[240:243], v[222:225], v[66:69]
	s_setprio 0
	s_mov_b32 m0, s26
	v_lshl_add_u64 v[250:251], v[244:245], 0, v[132:133]
	s_barrier
	ds_read_b128 v[192:195], v175 offset:16384
	ds_read_b128 v[200:203], v175 offset:18432
	ds_read_b128 v[210:213], v175 offset:20480
	ds_read_b128 v[218:221], v175 offset:22528
	ds_read_b128 v[196:199], v175 offset:17408
	ds_read_b128 v[204:207], v175 offset:19456
	ds_read_b128 v[214:217], v175 offset:21504
	ds_read_b128 v[222:225], v175 offset:23552
	global_load_lds_dwordx4 v[250:251], off
	v_lshl_add_u64 v[252:253], v[244:245], 0, v[142:143]
	s_mov_b32 m0, s41
	s_nop 0
	global_load_lds_dwordx4 v[252:253], off
	s_barrier
	s_setprio 1
	s_waitcnt lgkmcnt(7)
	v_mfma_f32_16x16x32_bf16 v[62:65], v[176:179], v[192:195], v[62:65]
	v_mfma_f32_16x16x32_bf16 v[58:61], v[184:187], v[192:195], v[58:61]
	s_waitcnt lgkmcnt(6)
	v_mfma_f32_16x16x32_bf16 v[54:57], v[176:179], v[200:203], v[54:57]
	v_mfma_f32_16x16x32_bf16 v[50:53], v[184:187], v[200:203], v[50:53]
	s_waitcnt lgkmcnt(5)
	v_mfma_f32_16x16x32_bf16 v[46:49], v[176:179], v[210:213], v[46:49]
	v_mfma_f32_16x16x32_bf16 v[42:45], v[184:187], v[210:213], v[42:45]
	s_waitcnt lgkmcnt(4)
	v_mfma_f32_16x16x32_bf16 v[38:41], v[176:179], v[218:221], v[38:41]
	v_mfma_f32_16x16x32_bf16 v[34:37], v[184:187], v[218:221], v[34:37]
	s_waitcnt lgkmcnt(3)
	v_mfma_f32_16x16x32_bf16 v[62:65], v[180:183], v[196:199], v[62:65]
	v_mfma_f32_16x16x32_bf16 v[58:61], v[188:191], v[196:199], v[58:61]
	s_waitcnt lgkmcnt(2)
	v_mfma_f32_16x16x32_bf16 v[54:57], v[180:183], v[204:207], v[54:57]
	v_mfma_f32_16x16x32_bf16 v[50:53], v[188:191], v[204:207], v[50:53]
	s_waitcnt lgkmcnt(1)
	v_mfma_f32_16x16x32_bf16 v[46:49], v[180:183], v[214:217], v[46:49]
	v_mfma_f32_16x16x32_bf16 v[42:45], v[188:191], v[214:217], v[42:45]
	s_waitcnt lgkmcnt(0)
	v_mfma_f32_16x16x32_bf16 v[38:41], v[180:183], v[222:225], v[38:41]
	v_mfma_f32_16x16x32_bf16 v[34:37], v[188:191], v[222:225], v[34:37]
	s_setprio 0
	s_barrier
	v_lshl_add_u64 v[176:177], v[170:171], 0, s[28:29]
	s_add_i32 s6, s7, s13
	v_lshl_add_u64 v[178:179], v[176:177], 0, v[132:133]
	s_mov_b32 m0, s6
	v_lshl_add_u64 v[176:177], v[176:177], 0, v[142:143]
	global_load_lds_dwordx4 v[178:179], off
	s_add_i32 m0, s6, 0x2000
	s_nop 0
	global_load_lds_dwordx4 v[176:177], off
	s_waitcnt vmcnt(6)
	s_barrier
	s_setprio 1
	v_mfma_f32_16x16x32_bf16 v[30:33], v[228:231], v[192:195], v[30:33]
	v_mfma_f32_16x16x32_bf16 v[26:29], v[236:239], v[192:195], v[26:29]
	v_mfma_f32_16x16x32_bf16 v[22:25], v[228:231], v[200:203], v[22:25]
	v_mfma_f32_16x16x32_bf16 v[18:21], v[236:239], v[200:203], v[18:21]
	v_mfma_f32_16x16x32_bf16 v[14:17], v[228:231], v[210:213], v[14:17]
	v_mfma_f32_16x16x32_bf16 v[10:13], v[236:239], v[210:213], v[10:13]
	v_mfma_f32_16x16x32_bf16 v[6:9], v[228:231], v[218:221], v[6:9]
	v_mfma_f32_16x16x32_bf16 v[2:5], v[236:239], v[218:221], v[2:5]
	v_mfma_f32_16x16x32_bf16 v[30:33], v[232:235], v[196:199], v[30:33]
	v_mfma_f32_16x16x32_bf16 v[26:29], v[240:243], v[196:199], v[26:29]
	v_mfma_f32_16x16x32_bf16 v[22:25], v[232:235], v[204:207], v[22:25]
	v_mfma_f32_16x16x32_bf16 v[18:21], v[240:243], v[204:207], v[18:21]
	v_mfma_f32_16x16x32_bf16 v[14:17], v[232:235], v[214:217], v[14:17]
	v_mfma_f32_16x16x32_bf16 v[10:13], v[240:243], v[214:217], v[10:13]
	v_mfma_f32_16x16x32_bf16 v[6:9], v[232:235], v[222:225], v[6:9]
	v_mfma_f32_16x16x32_bf16 v[2:5], v[240:243], v[222:225], v[2:5]
	s_setprio 0
	s_add_i32 s6, 0, 0x18000
	v_add_u32_e32 v188, s6, v174
	s_barrier
	ds_read_b128 v[176:179], v188
	ds_read_b128 v[184:187], v188 offset:2048
	ds_read_b128 v[180:183], v188 offset:1024
	ds_read_b128 v[188:191], v188 offset:3072
	v_lshl_add_u64 v[228:229], v[244:245], 0, s[28:29]
	s_mov_b32 m0, s42
	v_lshl_add_u64 v[230:231], v[228:229], 0, v[132:133]
	ds_read_b128 v[192:195], v175 offset:32768
	ds_read_b128 v[200:203], v175 offset:34816
	ds_read_b128 v[210:213], v175 offset:36864
	ds_read_b128 v[218:221], v175 offset:38912
	ds_read_b128 v[196:199], v175 offset:33792
	ds_read_b128 v[204:207], v175 offset:35840
	ds_read_b128 v[214:217], v175 offset:37888
	ds_read_b128 v[222:225], v175 offset:39936
	global_load_lds_dwordx4 v[230:231], off
	v_lshl_add_u64 v[228:229], v[228:229], 0, v[142:143]
	s_mov_b32 m0, s43
	s_nop 0
	global_load_lds_dwordx4 v[228:229], off
	s_waitcnt lgkmcnt(8)
	s_barrier
	s_setprio 1
	s_waitcnt lgkmcnt(7)
	v_mfma_f32_16x16x32_bf16 v[126:129], v[176:179], v[192:195], v[126:129]
	v_mfma_f32_16x16x32_bf16 v[122:125], v[184:187], v[192:195], v[122:125]
	s_waitcnt lgkmcnt(6)
	v_mfma_f32_16x16x32_bf16 v[118:121], v[176:179], v[200:203], v[118:121]
	v_mfma_f32_16x16x32_bf16 v[114:117], v[184:187], v[200:203], v[114:117]
	s_waitcnt lgkmcnt(5)
	v_mfma_f32_16x16x32_bf16 v[110:113], v[176:179], v[210:213], v[110:113]
	v_mfma_f32_16x16x32_bf16 v[106:109], v[184:187], v[210:213], v[106:109]
	s_waitcnt lgkmcnt(4)
	v_mfma_f32_16x16x32_bf16 v[102:105], v[176:179], v[218:221], v[102:105]
	v_mfma_f32_16x16x32_bf16 v[98:101], v[184:187], v[218:221], v[98:101]
	s_waitcnt lgkmcnt(3)
	v_mfma_f32_16x16x32_bf16 v[126:129], v[180:183], v[196:199], v[126:129]
	v_mfma_f32_16x16x32_bf16 v[122:125], v[188:191], v[196:199], v[122:125]
	s_waitcnt lgkmcnt(2)
	v_mfma_f32_16x16x32_bf16 v[118:121], v[180:183], v[204:207], v[118:121]
	v_mfma_f32_16x16x32_bf16 v[114:117], v[188:191], v[204:207], v[114:117]
	s_waitcnt lgkmcnt(1)
	v_mfma_f32_16x16x32_bf16 v[110:113], v[180:183], v[214:217], v[110:113]
	v_mfma_f32_16x16x32_bf16 v[106:109], v[188:191], v[214:217], v[106:109]
	s_waitcnt lgkmcnt(0)
	v_mfma_f32_16x16x32_bf16 v[102:105], v[180:183], v[222:225], v[102:105]
	v_mfma_f32_16x16x32_bf16 v[98:101], v[188:191], v[222:225], v[98:101]
	s_setprio 0
	s_barrier
	s_add_i32 s7, 0, 0x1c000
	s_add_i32 s6, s6, s13
	v_add_u32_e32 v208, s7, v174
	v_lshl_add_u64 v[244:245], v[246:247], 0, s[30:31]
	s_mov_b32 m0, s6
	ds_read_b128 v[228:231], v208
	ds_read_b128 v[236:239], v208 offset:2048
	ds_read_b128 v[232:235], v208 offset:1024
	ds_read_b128 v[240:243], v208 offset:3072
	global_load_lds_dwordx4 v[244:245], off
	v_lshl_add_u64 v[244:245], v[248:249], 0, s[30:31]
	s_add_i32 m0, s6, 0x2000
	s_nop 0
	global_load_lds_dwordx4 v[244:245], off
	s_barrier
	s_setprio 1
	s_waitcnt lgkmcnt(3)
	v_mfma_f32_16x16x32_bf16 v[94:97], v[228:231], v[192:195], v[94:97]
	s_waitcnt lgkmcnt(2)
	v_mfma_f32_16x16x32_bf16 v[90:93], v[236:239], v[192:195], v[90:93]
	v_mfma_f32_16x16x32_bf16 v[86:89], v[228:231], v[200:203], v[86:89]
	v_mfma_f32_16x16x32_bf16 v[82:85], v[236:239], v[200:203], v[82:85]
	v_mfma_f32_16x16x32_bf16 v[78:81], v[228:231], v[210:213], v[78:81]
	v_mfma_f32_16x16x32_bf16 v[74:77], v[236:239], v[210:213], v[74:77]
	v_mfma_f32_16x16x32_bf16 v[70:73], v[228:231], v[218:221], v[70:73]
	v_mfma_f32_16x16x32_bf16 v[66:69], v[236:239], v[218:221], v[66:69]
	s_waitcnt lgkmcnt(1)
	v_mfma_f32_16x16x32_bf16 v[94:97], v[232:235], v[196:199], v[94:97]
	s_waitcnt lgkmcnt(0)
	v_mfma_f32_16x16x32_bf16 v[90:93], v[240:243], v[196:199], v[90:93]
	v_mfma_f32_16x16x32_bf16 v[86:89], v[232:235], v[204:207], v[86:89]
	v_mfma_f32_16x16x32_bf16 v[82:85], v[240:243], v[204:207], v[82:85]
	v_mfma_f32_16x16x32_bf16 v[78:81], v[232:235], v[214:217], v[78:81]
	v_mfma_f32_16x16x32_bf16 v[74:77], v[240:243], v[214:217], v[74:77]
	v_mfma_f32_16x16x32_bf16 v[70:73], v[232:235], v[222:225], v[70:73]
	v_mfma_f32_16x16x32_bf16 v[66:69], v[240:243], v[222:225], v[66:69]
	s_setprio 0
	s_mov_b32 m0, s44
	v_lshl_add_u64 v[244:245], v[250:251], 0, s[30:31]
	s_barrier
	ds_read_b128 v[192:195], v175 offset:49152
	ds_read_b128 v[200:203], v175 offset:51200
	ds_read_b128 v[210:213], v175 offset:53248
	ds_read_b128 v[218:221], v175 offset:55296
	ds_read_b128 v[196:199], v175 offset:50176
	ds_read_b128 v[204:207], v175 offset:52224
	ds_read_b128 v[214:217], v175 offset:54272
	ds_read_b128 v[222:225], v175 offset:56320
	global_load_lds_dwordx4 v[244:245], off
	v_lshl_add_u64 v[244:245], v[252:253], 0, s[30:31]
	s_mov_b32 m0, s45
	s_nop 0
	global_load_lds_dwordx4 v[244:245], off
	s_barrier
	s_setprio 1
	s_waitcnt lgkmcnt(7)
	v_mfma_f32_16x16x32_bf16 v[62:65], v[176:179], v[192:195], v[62:65]
	v_mfma_f32_16x16x32_bf16 v[58:61], v[184:187], v[192:195], v[58:61]
	s_waitcnt lgkmcnt(6)
	v_mfma_f32_16x16x32_bf16 v[54:57], v[176:179], v[200:203], v[54:57]
	v_mfma_f32_16x16x32_bf16 v[50:53], v[184:187], v[200:203], v[50:53]
	s_waitcnt lgkmcnt(5)
	v_mfma_f32_16x16x32_bf16 v[46:49], v[176:179], v[210:213], v[46:49]
	v_mfma_f32_16x16x32_bf16 v[42:45], v[184:187], v[210:213], v[42:45]
	s_waitcnt lgkmcnt(4)
	v_mfma_f32_16x16x32_bf16 v[38:41], v[176:179], v[218:221], v[38:41]
	v_mfma_f32_16x16x32_bf16 v[34:37], v[184:187], v[218:221], v[34:37]
	s_waitcnt lgkmcnt(3)
	v_mfma_f32_16x16x32_bf16 v[62:65], v[180:183], v[196:199], v[62:65]
	v_mfma_f32_16x16x32_bf16 v[58:61], v[188:191], v[196:199], v[58:61]
	s_waitcnt lgkmcnt(2)
	v_mfma_f32_16x16x32_bf16 v[54:57], v[180:183], v[204:207], v[54:57]
	v_mfma_f32_16x16x32_bf16 v[50:53], v[188:191], v[204:207], v[50:53]
	s_waitcnt lgkmcnt(1)
	v_mfma_f32_16x16x32_bf16 v[46:49], v[180:183], v[214:217], v[46:49]
	v_mfma_f32_16x16x32_bf16 v[42:45], v[188:191], v[214:217], v[42:45]
	s_waitcnt lgkmcnt(0)
	v_mfma_f32_16x16x32_bf16 v[38:41], v[180:183], v[222:225], v[38:41]
	v_mfma_f32_16x16x32_bf16 v[34:37], v[188:191], v[222:225], v[34:37]
	s_setprio 0
	s_barrier
	v_lshl_add_u64 v[170:171], v[170:171], 0, s[34:35]
	s_add_i32 s6, s7, s13
	v_lshl_add_u64 v[176:177], v[170:171], 0, v[132:133]
	s_mov_b32 m0, s6
	v_lshl_add_u64 v[170:171], v[170:171], 0, v[142:143]
	global_load_lds_dwordx4 v[176:177], off
	s_add_i32 m0, s6, 0x2000
	s_nop 0
	global_load_lds_dwordx4 v[170:171], off
	s_waitcnt vmcnt(6)
	s_barrier
	s_setprio 1
	v_mfma_f32_16x16x32_bf16 v[30:33], v[228:231], v[192:195], v[30:33]
	v_mfma_f32_16x16x32_bf16 v[26:29], v[236:239], v[192:195], v[26:29]
	v_mfma_f32_16x16x32_bf16 v[22:25], v[228:231], v[200:203], v[22:25]
	v_mfma_f32_16x16x32_bf16 v[18:21], v[236:239], v[200:203], v[18:21]
	v_mfma_f32_16x16x32_bf16 v[14:17], v[228:231], v[210:213], v[14:17]
	v_mfma_f32_16x16x32_bf16 v[10:13], v[236:239], v[210:213], v[10:13]
	v_mfma_f32_16x16x32_bf16 v[6:9], v[228:231], v[218:221], v[6:9]
	v_mfma_f32_16x16x32_bf16 v[2:5], v[236:239], v[218:221], v[2:5]
	v_mfma_f32_16x16x32_bf16 v[30:33], v[232:235], v[196:199], v[30:33]
	v_mfma_f32_16x16x32_bf16 v[26:29], v[240:243], v[196:199], v[26:29]
	v_mfma_f32_16x16x32_bf16 v[22:25], v[232:235], v[204:207], v[22:25]
	v_mfma_f32_16x16x32_bf16 v[18:21], v[240:243], v[204:207], v[18:21]
	v_mfma_f32_16x16x32_bf16 v[14:17], v[232:235], v[214:217], v[14:17]
	v_mfma_f32_16x16x32_bf16 v[10:13], v[240:243], v[214:217], v[10:13]
	v_mfma_f32_16x16x32_bf16 v[6:9], v[232:235], v[222:225], v[6:9]
	v_mfma_f32_16x16x32_bf16 v[2:5], v[240:243], v[222:225], v[2:5]
	s_setprio 0
	s_add_i32 s46, s46, 2
	s_add_u32 s4, s4, 0x100
	s_addc_u32 s5, s5, 0
	s_cmp_lt_u32 s46, 14
	s_barrier
	s_cbranch_scc1 .LBB0_243
	s_waitcnt vmcnt(0)
	s_cmpk_gt_u32 s12, 0xff
	s_cbranch_scc1 .LBB0_246
	s_barrier

.LBB0_756:
	s_add_u32 s42, s6, 0xfbd20080
	s_addc_u32 s43, s7, -1
	s_cmp_lg_u32 s41, 20
	s_cselect_b32 s43, s43, 0
	s_cselect_b32 s42, s42, 0
	s_add_i32 s44, 0, 0x10000
	v_add_u32_e32 v152, s44, v168
	ds_read_b128 v[170:173], v152
	ds_read_b128 v[178:181], v152 offset:2048
	ds_read_b128 v[174:177], v152 offset:1024
	ds_read_b128 v[182:185], v152 offset:3072
	v_lshl_add_u64 v[206:207], v[146:147], 0, s[42:43]
	v_lshl_add_u64 v[152:153], v[144:145], 0, s[42:43]
	v_lshl_add_u64 v[222:223], v[148:149], 0, s[6:7]
	s_add_i32 m0, s34, 0xc000
	ds_read_b128 v[186:189], v169
	ds_read_b128 v[194:197], v169 offset:2048
	ds_read_b128 v[202:205], v169 offset:4096
	ds_read_b128 v[214:217], v169 offset:6144
	ds_read_b128 v[190:193], v169 offset:1024
	ds_read_b128 v[198:201], v169 offset:3072
	ds_read_b128 v[210:213], v169 offset:5120
	ds_read_b128 v[218:221], v169 offset:7168
	global_load_lds_dwordx4 v[222:223], off
	v_lshl_add_u64 v[222:223], v[150:151], 0, s[6:7]
	s_add_i32 m0, s34, 0xe000
	s_nop 0
	global_load_lds_dwordx4 v[222:223], off
	s_waitcnt lgkmcnt(8)
	s_barrier
	s_setprio 1
	s_waitcnt lgkmcnt(7)
	v_mfma_f32_16x16x32_bf16 v[126:129], v[170:173], v[186:189], v[126:129]
	v_mfma_f32_16x16x32_bf16 v[122:125], v[178:181], v[186:189], v[122:125]
	s_waitcnt lgkmcnt(6)
	v_mfma_f32_16x16x32_bf16 v[118:121], v[170:173], v[194:197], v[118:121]
	v_mfma_f32_16x16x32_bf16 v[114:117], v[178:181], v[194:197], v[114:117]
	s_waitcnt lgkmcnt(5)
	v_mfma_f32_16x16x32_bf16 v[110:113], v[170:173], v[202:205], v[110:113]
	v_mfma_f32_16x16x32_bf16 v[106:109], v[178:181], v[202:205], v[106:109]
	s_waitcnt lgkmcnt(4)
	v_mfma_f32_16x16x32_bf16 v[102:105], v[170:173], v[214:217], v[102:105]
	v_mfma_f32_16x16x32_bf16 v[98:101], v[178:181], v[214:217], v[98:101]
	s_waitcnt lgkmcnt(3)
	v_mfma_f32_16x16x32_bf16 v[126:129], v[174:177], v[190:193], v[126:129]
	v_mfma_f32_16x16x32_bf16 v[122:125], v[182:185], v[190:193], v[122:125]
	s_waitcnt lgkmcnt(2)
	v_mfma_f32_16x16x32_bf16 v[118:121], v[174:177], v[198:201], v[118:121]
	v_mfma_f32_16x16x32_bf16 v[114:117], v[182:185], v[198:201], v[114:117]
	s_waitcnt lgkmcnt(1)
	v_mfma_f32_16x16x32_bf16 v[110:113], v[174:177], v[210:213], v[110:113]
	v_mfma_f32_16x16x32_bf16 v[106:109], v[182:185], v[210:213], v[106:109]
	s_waitcnt lgkmcnt(0)
	v_mfma_f32_16x16x32_bf16 v[102:105], v[174:177], v[218:221], v[102:105]
	v_mfma_f32_16x16x32_bf16 v[98:101], v[182:185], v[218:221], v[98:101]
	s_setprio 0
	s_barrier
	s_add_i32 s42, 0, 0x14000
	s_add_i32 s43, s44, s33
	v_add_u32_e32 v208, s42, v168
	v_lshl_add_u64 v[240:241], v[152:153], 0, v[134:135]
	s_mov_b32 m0, s43
	ds_read_b128 v[222:225], v208
	ds_read_b128 v[232:235], v208 offset:2048
	ds_read_b128 v[228:231], v208 offset:1024
	ds_read_b128 v[236:239], v208 offset:3072
	global_load_lds_dwordx4 v[240:241], off
	v_lshl_add_u64 v[242:243], v[152:153], 0, v[142:143]
	s_add_i32 m0, s43, 0x2000
	s_nop 0
	global_load_lds_dwordx4 v[242:243], off
	s_barrier
	s_setprio 1
	s_waitcnt lgkmcnt(3)
	v_mfma_f32_16x16x32_bf16 v[94:97], v[222:225], v[186:189], v[94:97]
	s_waitcnt lgkmcnt(2)
	v_mfma_f32_16x16x32_bf16 v[90:93], v[232:235], v[186:189], v[90:93]
	v_mfma_f32_16x16x32_bf16 v[86:89], v[222:225], v[194:197], v[86:89]
	v_mfma_f32_16x16x32_bf16 v[82:85], v[232:235], v[194:197], v[82:85]
	v_mfma_f32_16x16x32_bf16 v[78:81], v[222:225], v[202:205], v[78:81]
	v_mfma_f32_16x16x32_bf16 v[74:77], v[232:235], v[202:205], v[74:77]
	v_mfma_f32_16x16x32_bf16 v[70:73], v[222:225], v[214:217], v[70:73]
	v_mfma_f32_16x16x32_bf16 v[66:69], v[232:235], v[214:217], v[66:69]
	s_waitcnt lgkmcnt(1)
	v_mfma_f32_16x16x32_bf16 v[94:97], v[228:231], v[190:193], v[94:97]
	s_waitcnt lgkmcnt(0)
	v_mfma_f32_16x16x32_bf16 v[90:93], v[236:239], v[190:193], v[90:93]
	v_mfma_f32_16x16x32_bf16 v[86:89], v[228:231], v[198:201], v[86:89]
	v_mfma_f32_16x16x32_bf16 v[82:85], v[236:239], v[198:201], v[82:85]
	v_mfma_f32_16x16x32_bf16 v[78:81], v[228:231], v[210:213], v[78:81]
	v_mfma_f32_16x16x32_bf16 v[74:77], v[236:239], v[210:213], v[74:77]
	v_mfma_f32_16x16x32_bf16 v[70:73], v[228:231], v[218:221], v[70:73]
	v_mfma_f32_16x16x32_bf16 v[66:69], v[236:239], v[218:221], v[66:69]
	s_setprio 0
	s_mov_b32 m0, s34
	v_lshl_add_u64 v[244:245], v[206:207], 0, v[134:135]
	s_barrier
	ds_read_b128 v[186:189], v169 offset:16384
	ds_read_b128 v[194:197], v169 offset:18432
	ds_read_b128 v[202:205], v169 offset:20480
	ds_read_b128 v[214:217], v169 offset:22528
	ds_read_b128 v[190:193], v169 offset:17408
	ds_read_b128 v[198:201], v169 offset:19456
	ds_read_b128 v[210:213], v169 offset:21504
	ds_read_b128 v[218:221], v169 offset:23552
	global_load_lds_dwordx4 v[244:245], off
	v_lshl_add_u64 v[246:247], v[206:207], 0, v[142:143]
	s_mov_b32 m0, s35
	s_nop 0
	global_load_lds_dwordx4 v[246:247], off
	s_barrier
	s_setprio 1
	s_waitcnt lgkmcnt(7)
	v_mfma_f32_16x16x32_bf16 v[62:65], v[170:173], v[186:189], v[62:65]
	v_mfma_f32_16x16x32_bf16 v[58:61], v[178:181], v[186:189], v[58:61]
	s_waitcnt lgkmcnt(6)
	v_mfma_f32_16x16x32_bf16 v[54:57], v[170:173], v[194:197], v[54:57]
	v_mfma_f32_16x16x32_bf16 v[50:53], v[178:181], v[194:197], v[50:53]
	s_waitcnt lgkmcnt(5)
	v_mfma_f32_16x16x32_bf16 v[46:49], v[170:173], v[202:205], v[46:49]
	v_mfma_f32_16x16x32_bf16 v[42:45], v[178:181], v[202:205], v[42:45]
	s_waitcnt lgkmcnt(4)
	v_mfma_f32_16x16x32_bf16 v[38:41], v[170:173], v[214:217], v[38:41]
	v_mfma_f32_16x16x32_bf16 v[34:37], v[178:181], v[214:217], v[34:37]
	s_waitcnt lgkmcnt(3)
	v_mfma_f32_16x16x32_bf16 v[62:65], v[174:177], v[190:193], v[62:65]
	v_mfma_f32_16x16x32_bf16 v[58:61], v[182:185], v[190:193], v[58:61]
	s_waitcnt lgkmcnt(2)
	v_mfma_f32_16x16x32_bf16 v[54:57], v[174:177], v[198:201], v[54:57]
	v_mfma_f32_16x16x32_bf16 v[50:53], v[182:185], v[198:201], v[50:53]
	s_waitcnt lgkmcnt(1)
	v_mfma_f32_16x16x32_bf16 v[46:49], v[174:177], v[210:213], v[46:49]
	v_mfma_f32_16x16x32_bf16 v[42:45], v[182:185], v[210:213], v[42:45]
	s_waitcnt lgkmcnt(0)
	v_mfma_f32_16x16x32_bf16 v[38:41], v[174:177], v[218:221], v[38:41]
	v_mfma_f32_16x16x32_bf16 v[34:37], v[182:185], v[218:221], v[34:37]
	s_setprio 0
	s_barrier
	v_lshl_add_u64 v[170:171], v[152:153], 0, s[14:15]
	s_add_i32 s42, s42, s33
	v_lshl_add_u64 v[172:173], v[170:171], 0, v[134:135]
	s_mov_b32 m0, s42
	v_lshl_add_u64 v[170:171], v[170:171], 0, v[142:143]
	global_load_lds_dwordx4 v[172:173], off
	s_add_i32 m0, s42, 0x2000
	s_nop 0
	global_load_lds_dwordx4 v[170:171], off
	s_waitcnt vmcnt(6)
	s_barrier
	s_setprio 1
	v_mfma_f32_16x16x32_bf16 v[30:33], v[222:225], v[186:189], v[30:33]
	v_mfma_f32_16x16x32_bf16 v[26:29], v[232:235], v[186:189], v[26:29]
	v_mfma_f32_16x16x32_bf16 v[22:25], v[222:225], v[194:197], v[22:25]
	v_mfma_f32_16x16x32_bf16 v[18:21], v[232:235], v[194:197], v[18:21]
	v_mfma_f32_16x16x32_bf16 v[14:17], v[222:225], v[202:205], v[14:17]
	v_mfma_f32_16x16x32_bf16 v[10:13], v[232:235], v[202:205], v[10:13]
	v_mfma_f32_16x16x32_bf16 v[6:9], v[222:225], v[214:217], v[6:9]
	v_mfma_f32_16x16x32_bf16 v[2:5], v[232:235], v[214:217], v[2:5]
	v_mfma_f32_16x16x32_bf16 v[30:33], v[228:231], v[190:193], v[30:33]
	v_mfma_f32_16x16x32_bf16 v[26:29], v[236:239], v[190:193], v[26:29]
	v_mfma_f32_16x16x32_bf16 v[22:25], v[228:231], v[198:201], v[22:25]
	v_mfma_f32_16x16x32_bf16 v[18:21], v[236:239], v[198:201], v[18:21]
	v_mfma_f32_16x16x32_bf16 v[14:17], v[228:231], v[210:213], v[14:17]
	v_mfma_f32_16x16x32_bf16 v[10:13], v[236:239], v[210:213], v[10:13]
	v_mfma_f32_16x16x32_bf16 v[6:9], v[228:231], v[218:221], v[6:9]
	v_mfma_f32_16x16x32_bf16 v[2:5], v[236:239], v[218:221], v[2:5]
	s_setprio 0
	s_add_i32 s42, 0, 0x18000
	v_add_u32_e32 v182, s42, v168
	s_barrier
	ds_read_b128 v[170:173], v182
	ds_read_b128 v[178:181], v182 offset:2048
	ds_read_b128 v[174:177], v182 offset:1024
	ds_read_b128 v[182:185], v182 offset:3072
	v_lshl_add_u64 v[206:207], v[206:207], 0, s[14:15]
	s_mov_b32 m0, s37
	v_lshl_add_u64 v[222:223], v[206:207], 0, v[134:135]
	ds_read_b128 v[186:189], v169 offset:32768
	ds_read_b128 v[194:197], v169 offset:34816
	ds_read_b128 v[202:205], v169 offset:36864
	ds_read_b128 v[214:217], v169 offset:38912
	ds_read_b128 v[190:193], v169 offset:33792
	ds_read_b128 v[198:201], v169 offset:35840
	ds_read_b128 v[210:213], v169 offset:37888
	ds_read_b128 v[218:221], v169 offset:39936
	global_load_lds_dwordx4 v[222:223], off
	v_lshl_add_u64 v[206:207], v[206:207], 0, v[142:143]
	s_mov_b32 m0, s38
	s_nop 0
	global_load_lds_dwordx4 v[206:207], off
	s_waitcnt lgkmcnt(8)
	s_barrier
	s_setprio 1
	s_waitcnt lgkmcnt(7)
	v_mfma_f32_16x16x32_bf16 v[126:129], v[170:173], v[186:189], v[126:129]
	v_mfma_f32_16x16x32_bf16 v[122:125], v[178:181], v[186:189], v[122:125]
	s_waitcnt lgkmcnt(6)
	v_mfma_f32_16x16x32_bf16 v[118:121], v[170:173], v[194:197], v[118:121]
	v_mfma_f32_16x16x32_bf16 v[114:117], v[178:181], v[194:197], v[114:117]
	s_waitcnt lgkmcnt(5)
	v_mfma_f32_16x16x32_bf16 v[110:113], v[170:173], v[202:205], v[110:113]
	v_mfma_f32_16x16x32_bf16 v[106:109], v[178:181], v[202:205], v[106:109]
	s_waitcnt lgkmcnt(4)
	v_mfma_f32_16x16x32_bf16 v[102:105], v[170:173], v[214:217], v[102:105]
	v_mfma_f32_16x16x32_bf16 v[98:101], v[178:181], v[214:217], v[98:101]
	s_waitcnt lgkmcnt(3)
	v_mfma_f32_16x16x32_bf16 v[126:129], v[174:177], v[190:193], v[126:129]
	v_mfma_f32_16x16x32_bf16 v[122:125], v[182:185], v[190:193], v[122:125]
	s_waitcnt lgkmcnt(2)
	v_mfma_f32_16x16x32_bf16 v[118:121], v[174:177], v[198:201], v[118:121]
	v_mfma_f32_16x16x32_bf16 v[114:117], v[182:185], v[198:201], v[114:117]
	s_waitcnt lgkmcnt(1)
	v_mfma_f32_16x16x32_bf16 v[110:113], v[174:177], v[210:213], v[110:113]
	v_mfma_f32_16x16x32_bf16 v[106:109], v[182:185], v[210:213], v[106:109]
	s_waitcnt lgkmcnt(0)
	v_mfma_f32_16x16x32_bf16 v[102:105], v[174:177], v[218:221], v[102:105]
	v_mfma_f32_16x16x32_bf16 v[98:101], v[182:185], v[218:221], v[98:101]
	s_setprio 0
	s_barrier
	s_add_i32 s43, 0, 0x1c000
	v_add_u32_e32 v206, s43, v168
	s_add_i32 s42, s42, s33
	ds_read_b128 v[222:225], v206
	ds_read_b128 v[232:235], v206 offset:2048
	ds_read_b128 v[228:231], v206 offset:1024
	ds_read_b128 v[236:239], v206 offset:3072
	v_lshl_add_u64 v[206:207], v[240:241], 0, s[16:17]
	s_mov_b32 m0, s42
	s_nop 0
	global_load_lds_dwordx4 v[206:207], off
	v_lshl_add_u64 v[206:207], v[242:243], 0, s[16:17]
	s_add_i32 m0, s42, 0x2000
	s_nop 0
	global_load_lds_dwordx4 v[206:207], off
	s_barrier
	s_setprio 1
	s_waitcnt lgkmcnt(3)
	v_mfma_f32_16x16x32_bf16 v[94:97], v[222:225], v[186:189], v[94:97]
	s_waitcnt lgkmcnt(2)
	v_mfma_f32_16x16x32_bf16 v[90:93], v[232:235], v[186:189], v[90:93]
	v_mfma_f32_16x16x32_bf16 v[86:89], v[222:225], v[194:197], v[86:89]
	v_mfma_f32_16x16x32_bf16 v[82:85], v[232:235], v[194:197], v[82:85]
	v_mfma_f32_16x16x32_bf16 v[78:81], v[222:225], v[202:205], v[78:81]
	v_mfma_f32_16x16x32_bf16 v[74:77], v[232:235], v[202:205], v[74:77]
	v_mfma_f32_16x16x32_bf16 v[70:73], v[222:225], v[214:217], v[70:73]
	v_mfma_f32_16x16x32_bf16 v[66:69], v[232:235], v[214:217], v[66:69]
	s_waitcnt lgkmcnt(1)
	v_mfma_f32_16x16x32_bf16 v[94:97], v[228:231], v[190:193], v[94:97]
	s_waitcnt lgkmcnt(0)
	v_mfma_f32_16x16x32_bf16 v[90:93], v[236:239], v[190:193], v[90:93]
	v_mfma_f32_16x16x32_bf16 v[86:89], v[228:231], v[198:201], v[86:89]
	v_mfma_f32_16x16x32_bf16 v[82:85], v[236:239], v[198:201], v[82:85]
	v_mfma_f32_16x16x32_bf16 v[78:81], v[228:231], v[210:213], v[78:81]
	v_mfma_f32_16x16x32_bf16 v[74:77], v[236:239], v[210:213], v[74:77]
	v_mfma_f32_16x16x32_bf16 v[70:73], v[228:231], v[218:221], v[70:73]
	v_mfma_f32_16x16x32_bf16 v[66:69], v[236:239], v[218:221], v[66:69]
	s_setprio 0
	s_mov_b32 m0, s39
	v_lshl_add_u64 v[206:207], v[244:245], 0, s[16:17]
	s_barrier
	ds_read_b128 v[186:189], v169 offset:49152
	ds_read_b128 v[194:197], v169 offset:51200
	ds_read_b128 v[202:205], v169 offset:53248
	ds_read_b128 v[214:217], v169 offset:55296
	ds_read_b128 v[190:193], v169 offset:50176
	ds_read_b128 v[198:201], v169 offset:52224
	ds_read_b128 v[210:213], v169 offset:54272
	ds_read_b128 v[218:221], v169 offset:56320
	global_load_lds_dwordx4 v[206:207], off
	v_lshl_add_u64 v[206:207], v[246:247], 0, s[16:17]
	s_mov_b32 m0, s40
	s_nop 0
	global_load_lds_dwordx4 v[206:207], off
	s_barrier
	s_setprio 1
	s_waitcnt lgkmcnt(7)
	v_mfma_f32_16x16x32_bf16 v[62:65], v[170:173], v[186:189], v[62:65]
	v_mfma_f32_16x16x32_bf16 v[58:61], v[178:181], v[186:189], v[58:61]
	s_waitcnt lgkmcnt(6)
	v_mfma_f32_16x16x32_bf16 v[54:57], v[170:173], v[194:197], v[54:57]
	v_mfma_f32_16x16x32_bf16 v[50:53], v[178:181], v[194:197], v[50:53]
	s_waitcnt lgkmcnt(5)
	v_mfma_f32_16x16x32_bf16 v[46:49], v[170:173], v[202:205], v[46:49]
	v_mfma_f32_16x16x32_bf16 v[42:45], v[178:181], v[202:205], v[42:45]
	s_waitcnt lgkmcnt(4)
	v_mfma_f32_16x16x32_bf16 v[38:41], v[170:173], v[214:217], v[38:41]
	v_mfma_f32_16x16x32_bf16 v[34:37], v[178:181], v[214:217], v[34:37]
	s_waitcnt lgkmcnt(3)
	v_mfma_f32_16x16x32_bf16 v[62:65], v[174:177], v[190:193], v[62:65]
	v_mfma_f32_16x16x32_bf16 v[58:61], v[182:185], v[190:193], v[58:61]
	s_waitcnt lgkmcnt(2)
	v_mfma_f32_16x16x32_bf16 v[54:57], v[174:177], v[198:201], v[54:57]
	v_mfma_f32_16x16x32_bf16 v[50:53], v[182:185], v[198:201], v[50:53]
	s_waitcnt lgkmcnt(1)
	v_mfma_f32_16x16x32_bf16 v[46:49], v[174:177], v[210:213], v[46:49]
	v_mfma_f32_16x16x32_bf16 v[42:45], v[182:185], v[210:213], v[42:45]
	s_waitcnt lgkmcnt(0)
	v_mfma_f32_16x16x32_bf16 v[38:41], v[174:177], v[218:221], v[38:41]
	v_mfma_f32_16x16x32_bf16 v[34:37], v[182:185], v[218:221], v[34:37]
	s_setprio 0
	s_barrier
	v_lshl_add_u64 v[152:153], v[152:153], 0, s[18:19]
	s_add_i32 s42, s43, s33
	v_lshl_add_u64 v[170:171], v[152:153], 0, v[134:135]
	s_mov_b32 m0, s42
	v_lshl_add_u64 v[152:153], v[152:153], 0, v[142:143]
	global_load_lds_dwordx4 v[170:171], off
	s_add_i32 m0, s42, 0x2000
	s_nop 0
	global_load_lds_dwordx4 v[152:153], off
	s_waitcnt vmcnt(6)
	s_barrier
	s_setprio 1
	v_mfma_f32_16x16x32_bf16 v[30:33], v[222:225], v[186:189], v[30:33]
	v_mfma_f32_16x16x32_bf16 v[26:29], v[232:235], v[186:189], v[26:29]
	v_mfma_f32_16x16x32_bf16 v[22:25], v[222:225], v[194:197], v[22:25]
	v_mfma_f32_16x16x32_bf16 v[18:21], v[232:235], v[194:197], v[18:21]
	v_mfma_f32_16x16x32_bf16 v[14:17], v[222:225], v[202:205], v[14:17]
	v_mfma_f32_16x16x32_bf16 v[10:13], v[232:235], v[202:205], v[10:13]
	v_mfma_f32_16x16x32_bf16 v[6:9], v[222:225], v[214:217], v[6:9]
	v_mfma_f32_16x16x32_bf16 v[2:5], v[232:235], v[214:217], v[2:5]
	v_mfma_f32_16x16x32_bf16 v[30:33], v[228:231], v[190:193], v[30:33]
	v_mfma_f32_16x16x32_bf16 v[26:29], v[236:239], v[190:193], v[26:29]
	v_mfma_f32_16x16x32_bf16 v[22:25], v[228:231], v[198:201], v[22:25]
	v_mfma_f32_16x16x32_bf16 v[18:21], v[236:239], v[198:201], v[18:21]
	v_mfma_f32_16x16x32_bf16 v[14:17], v[228:231], v[210:213], v[14:17]
	v_mfma_f32_16x16x32_bf16 v[10:13], v[236:239], v[210:213], v[10:13]
	v_mfma_f32_16x16x32_bf16 v[6:9], v[228:231], v[218:221], v[6:9]
	v_mfma_f32_16x16x32_bf16 v[2:5], v[236:239], v[218:221], v[2:5]
	s_setprio 0
	s_add_i32 s41, s41, 2
	s_add_u32 s6, s6, 0x100
	s_addc_u32 s7, s7, 0
	s_cmp_lt_u32 s41, 22
	s_barrier
	s_cbranch_scc1 .LBB0_756
	s_waitcnt vmcnt(0)
	s_cmpk_gt_u32 s31, 0xff
	s_cbranch_scc1 .LBB0_759
	s_barrier

.LBB0_914:
	s_cmpk_eq_i32 s6, 0x700
	v_lshl_add_u64 v[170:171], v[150:151], 0, s[6:7]
	v_lshl_add_u64 v[170:171], v[170:171], 0, s[20:21]
	s_cselect_b64 vcc, -1, 0
	s_add_i32 s9, 0, 0x10000
	v_cndmask_b32_e32 v245, v171, v149, vcc
	v_add_u32_e32 v171, s9, v173
	ds_read_b128 v[176:179], v171
	ds_read_b128 v[184:187], v171 offset:2048
	ds_read_b128 v[180:183], v171 offset:1024
	ds_read_b128 v[188:191], v171 offset:3072
	v_cndmask_b32_e32 v244, v170, v148, vcc
	v_lshl_add_u64 v[170:171], v[168:169], 0, s[6:7]
	v_cndmask_b32_e32 v171, v171, v147, vcc
	v_cndmask_b32_e32 v170, v170, v146, vcc
	v_lshl_add_u64 v[228:229], v[152:153], 0, s[6:7]
	s_add_i32 m0, s34, 0xc000
	ds_read_b128 v[192:195], v174
	ds_read_b128 v[200:203], v174 offset:2048
	ds_read_b128 v[210:213], v174 offset:4096
	ds_read_b128 v[218:221], v174 offset:6144
	ds_read_b128 v[196:199], v174 offset:1024
	ds_read_b128 v[204:207], v174 offset:3072
	ds_read_b128 v[214:217], v174 offset:5120
	ds_read_b128 v[222:225], v174 offset:7168
	global_load_lds_dwordx4 v[228:229], off
	v_lshl_add_u64 v[228:229], v[166:167], 0, s[6:7]
	s_add_i32 m0, s34, 0xe000
	s_nop 0
	global_load_lds_dwordx4 v[228:229], off
	s_waitcnt lgkmcnt(8)
	s_barrier
	s_setprio 1
	s_waitcnt lgkmcnt(7)
	v_mfma_f32_16x16x32_bf16 v[126:129], v[176:179], v[192:195], v[126:129]
	v_mfma_f32_16x16x32_bf16 v[122:125], v[184:187], v[192:195], v[122:125]
	s_waitcnt lgkmcnt(6)
	v_mfma_f32_16x16x32_bf16 v[118:121], v[176:179], v[200:203], v[118:121]
	v_mfma_f32_16x16x32_bf16 v[114:117], v[184:187], v[200:203], v[114:117]
	s_waitcnt lgkmcnt(5)
	v_mfma_f32_16x16x32_bf16 v[110:113], v[176:179], v[210:213], v[110:113]
	v_mfma_f32_16x16x32_bf16 v[106:109], v[184:187], v[210:213], v[106:109]
	s_waitcnt lgkmcnt(4)
	v_mfma_f32_16x16x32_bf16 v[102:105], v[176:179], v[218:221], v[102:105]
	v_mfma_f32_16x16x32_bf16 v[98:101], v[184:187], v[218:221], v[98:101]
	s_waitcnt lgkmcnt(3)
	v_mfma_f32_16x16x32_bf16 v[126:129], v[180:183], v[196:199], v[126:129]
	v_mfma_f32_16x16x32_bf16 v[122:125], v[188:191], v[196:199], v[122:125]
	s_waitcnt lgkmcnt(2)
	v_mfma_f32_16x16x32_bf16 v[118:121], v[180:183], v[204:207], v[118:121]
	v_mfma_f32_16x16x32_bf16 v[114:117], v[188:191], v[204:207], v[114:117]
	s_waitcnt lgkmcnt(1)
	v_mfma_f32_16x16x32_bf16 v[110:113], v[180:183], v[214:217], v[110:113]
	v_mfma_f32_16x16x32_bf16 v[106:109], v[188:191], v[214:217], v[106:109]
	s_waitcnt lgkmcnt(0)
	v_mfma_f32_16x16x32_bf16 v[102:105], v[180:183], v[222:225], v[102:105]
	v_mfma_f32_16x16x32_bf16 v[98:101], v[188:191], v[222:225], v[98:101]
	s_setprio 0
	s_barrier
	s_add_i32 s57, 0, 0x14000
	s_add_i32 s9, s9, s39
	v_add_u32_e32 v175, s57, v173
	v_lshl_add_u64 v[246:247], v[170:171], 0, v[134:135]
	s_mov_b32 m0, s9
	ds_read_b128 v[228:231], v175
	ds_read_b128 v[236:239], v175 offset:2048
	ds_read_b128 v[232:235], v175 offset:1024
	ds_read_b128 v[240:243], v175 offset:3072
	global_load_lds_dwordx4 v[246:247], off
	v_lshl_add_u64 v[248:249], v[170:171], 0, v[144:145]
	s_add_i32 m0, s9, 0x2000
	s_nop 0
	global_load_lds_dwordx4 v[248:249], off
	s_barrier
	s_setprio 1
	s_waitcnt lgkmcnt(3)
	v_mfma_f32_16x16x32_bf16 v[94:97], v[228:231], v[192:195], v[94:97]
	s_waitcnt lgkmcnt(2)
	v_mfma_f32_16x16x32_bf16 v[90:93], v[236:239], v[192:195], v[90:93]
	v_mfma_f32_16x16x32_bf16 v[86:89], v[228:231], v[200:203], v[86:89]
	v_mfma_f32_16x16x32_bf16 v[82:85], v[236:239], v[200:203], v[82:85]
	v_mfma_f32_16x16x32_bf16 v[78:81], v[228:231], v[210:213], v[78:81]
	v_mfma_f32_16x16x32_bf16 v[74:77], v[236:239], v[210:213], v[74:77]
	v_mfma_f32_16x16x32_bf16 v[70:73], v[228:231], v[218:221], v[70:73]
	v_mfma_f32_16x16x32_bf16 v[66:69], v[236:239], v[218:221], v[66:69]
	s_waitcnt lgkmcnt(1)
	v_mfma_f32_16x16x32_bf16 v[94:97], v[232:235], v[196:199], v[94:97]
	s_waitcnt lgkmcnt(0)
	v_mfma_f32_16x16x32_bf16 v[90:93], v[240:243], v[196:199], v[90:93]
	v_mfma_f32_16x16x32_bf16 v[86:89], v[232:235], v[204:207], v[86:89]
	v_mfma_f32_16x16x32_bf16 v[82:85], v[240:243], v[204:207], v[82:85]
	v_mfma_f32_16x16x32_bf16 v[78:81], v[232:235], v[214:217], v[78:81]
	v_mfma_f32_16x16x32_bf16 v[74:77], v[240:243], v[214:217], v[74:77]
	v_mfma_f32_16x16x32_bf16 v[70:73], v[232:235], v[222:225], v[70:73]
	v_mfma_f32_16x16x32_bf16 v[66:69], v[240:243], v[222:225], v[66:69]
	s_setprio 0
	s_mov_b32 m0, s34
	v_lshl_add_u64 v[250:251], v[244:245], 0, v[134:135]
	s_barrier
	ds_read_b128 v[192:195], v174 offset:16384
	ds_read_b128 v[200:203], v174 offset:18432
	ds_read_b128 v[210:213], v174 offset:20480
	ds_read_b128 v[218:221], v174 offset:22528
	ds_read_b128 v[196:199], v174 offset:17408
	ds_read_b128 v[204:207], v174 offset:19456
	ds_read_b128 v[214:217], v174 offset:21504
	ds_read_b128 v[222:225], v174 offset:23552
	global_load_lds_dwordx4 v[250:251], off
	v_lshl_add_u64 v[252:253], v[244:245], 0, v[144:145]
	s_mov_b32 m0, s41
	s_nop 0
	global_load_lds_dwordx4 v[252:253], off
	s_barrier
	s_setprio 1
	s_waitcnt lgkmcnt(7)
	v_mfma_f32_16x16x32_bf16 v[62:65], v[176:179], v[192:195], v[62:65]
	v_mfma_f32_16x16x32_bf16 v[58:61], v[184:187], v[192:195], v[58:61]
	s_waitcnt lgkmcnt(6)
	v_mfma_f32_16x16x32_bf16 v[54:57], v[176:179], v[200:203], v[54:57]
	v_mfma_f32_16x16x32_bf16 v[50:53], v[184:187], v[200:203], v[50:53]
	s_waitcnt lgkmcnt(5)
	v_mfma_f32_16x16x32_bf16 v[46:49], v[176:179], v[210:213], v[46:49]
	v_mfma_f32_16x16x32_bf16 v[42:45], v[184:187], v[210:213], v[42:45]
	s_waitcnt lgkmcnt(4)
	v_mfma_f32_16x16x32_bf16 v[38:41], v[176:179], v[218:221], v[38:41]
	v_mfma_f32_16x16x32_bf16 v[34:37], v[184:187], v[218:221], v[34:37]
	s_waitcnt lgkmcnt(3)
	v_mfma_f32_16x16x32_bf16 v[62:65], v[180:183], v[196:199], v[62:65]
	v_mfma_f32_16x16x32_bf16 v[58:61], v[188:191], v[196:199], v[58:61]
	s_waitcnt lgkmcnt(2)
	v_mfma_f32_16x16x32_bf16 v[54:57], v[180:183], v[204:207], v[54:57]
	v_mfma_f32_16x16x32_bf16 v[50:53], v[188:191], v[204:207], v[50:53]
	s_waitcnt lgkmcnt(1)
	v_mfma_f32_16x16x32_bf16 v[46:49], v[180:183], v[214:217], v[46:49]
	v_mfma_f32_16x16x32_bf16 v[42:45], v[188:191], v[214:217], v[42:45]
	s_waitcnt lgkmcnt(0)
	v_mfma_f32_16x16x32_bf16 v[38:41], v[180:183], v[222:225], v[38:41]
	v_mfma_f32_16x16x32_bf16 v[34:37], v[188:191], v[222:225], v[34:37]
	s_setprio 0
	s_barrier
	v_lshl_add_u64 v[176:177], v[170:171], 0, s[10:11]
	s_add_i32 s9, s57, s39
	v_lshl_add_u64 v[178:179], v[176:177], 0, v[134:135]
	s_mov_b32 m0, s9
	v_lshl_add_u64 v[176:177], v[176:177], 0, v[144:145]
	global_load_lds_dwordx4 v[178:179], off
	s_add_i32 m0, s9, 0x2000
	s_nop 0
	global_load_lds_dwordx4 v[176:177], off
	s_waitcnt vmcnt(6)
	s_barrier
	s_setprio 1
	v_mfma_f32_16x16x32_bf16 v[30:33], v[228:231], v[192:195], v[30:33]
	v_mfma_f32_16x16x32_bf16 v[26:29], v[236:239], v[192:195], v[26:29]
	v_mfma_f32_16x16x32_bf16 v[22:25], v[228:231], v[200:203], v[22:25]
	v_mfma_f32_16x16x32_bf16 v[18:21], v[236:239], v[200:203], v[18:21]
	v_mfma_f32_16x16x32_bf16 v[14:17], v[228:231], v[210:213], v[14:17]
	v_mfma_f32_16x16x32_bf16 v[10:13], v[236:239], v[210:213], v[10:13]
	v_mfma_f32_16x16x32_bf16 v[6:9], v[228:231], v[218:221], v[6:9]
	v_mfma_f32_16x16x32_bf16 v[2:5], v[236:239], v[218:221], v[2:5]
	v_mfma_f32_16x16x32_bf16 v[30:33], v[232:235], v[196:199], v[30:33]
	v_mfma_f32_16x16x32_bf16 v[26:29], v[240:243], v[196:199], v[26:29]
	v_mfma_f32_16x16x32_bf16 v[22:25], v[232:235], v[204:207], v[22:25]
	v_mfma_f32_16x16x32_bf16 v[18:21], v[240:243], v[204:207], v[18:21]
	v_mfma_f32_16x16x32_bf16 v[14:17], v[232:235], v[214:217], v[14:17]
	v_mfma_f32_16x16x32_bf16 v[10:13], v[240:243], v[214:217], v[10:13]
	v_mfma_f32_16x16x32_bf16 v[6:9], v[232:235], v[222:225], v[6:9]
	v_mfma_f32_16x16x32_bf16 v[2:5], v[240:243], v[222:225], v[2:5]
	s_setprio 0
	s_add_i32 s9, 0, 0x18000
	v_add_u32_e32 v175, s9, v173
	s_barrier
	ds_read_b128 v[176:179], v175
	ds_read_b128 v[184:187], v175 offset:2048
	ds_read_b128 v[180:183], v175 offset:1024
	ds_read_b128 v[188:191], v175 offset:3072
	v_lshl_add_u64 v[228:229], v[244:245], 0, s[10:11]
	s_mov_b32 m0, s42
	v_lshl_add_u64 v[230:231], v[228:229], 0, v[134:135]
	ds_read_b128 v[192:195], v174 offset:32768
	ds_read_b128 v[200:203], v174 offset:34816
	ds_read_b128 v[210:213], v174 offset:36864
	ds_read_b128 v[218:221], v174 offset:38912
	ds_read_b128 v[196:199], v174 offset:33792
	ds_read_b128 v[204:207], v174 offset:35840
	ds_read_b128 v[214:217], v174 offset:37888
	ds_read_b128 v[222:225], v174 offset:39936
	global_load_lds_dwordx4 v[230:231], off
	v_lshl_add_u64 v[228:229], v[228:229], 0, v[144:145]
	s_mov_b32 m0, s43
	s_nop 0
	global_load_lds_dwordx4 v[228:229], off
	s_waitcnt lgkmcnt(8)
	s_barrier
	s_setprio 1
	s_waitcnt lgkmcnt(7)
	v_mfma_f32_16x16x32_bf16 v[126:129], v[176:179], v[192:195], v[126:129]
	v_mfma_f32_16x16x32_bf16 v[122:125], v[184:187], v[192:195], v[122:125]
	s_waitcnt lgkmcnt(6)
	v_mfma_f32_16x16x32_bf16 v[118:121], v[176:179], v[200:203], v[118:121]
	v_mfma_f32_16x16x32_bf16 v[114:117], v[184:187], v[200:203], v[114:117]
	s_waitcnt lgkmcnt(5)
	v_mfma_f32_16x16x32_bf16 v[110:113], v[176:179], v[210:213], v[110:113]
	v_mfma_f32_16x16x32_bf16 v[106:109], v[184:187], v[210:213], v[106:109]
	s_waitcnt lgkmcnt(4)
	v_mfma_f32_16x16x32_bf16 v[102:105], v[176:179], v[218:221], v[102:105]
	v_mfma_f32_16x16x32_bf16 v[98:101], v[184:187], v[218:221], v[98:101]
	s_waitcnt lgkmcnt(3)
	v_mfma_f32_16x16x32_bf16 v[126:129], v[180:183], v[196:199], v[126:129]
	v_mfma_f32_16x16x32_bf16 v[122:125], v[188:191], v[196:199], v[122:125]
	s_waitcnt lgkmcnt(2)
	v_mfma_f32_16x16x32_bf16 v[118:121], v[180:183], v[204:207], v[118:121]
	v_mfma_f32_16x16x32_bf16 v[114:117], v[188:191], v[204:207], v[114:117]
	s_waitcnt lgkmcnt(1)
	v_mfma_f32_16x16x32_bf16 v[110:113], v[180:183], v[214:217], v[110:113]
	v_mfma_f32_16x16x32_bf16 v[106:109], v[188:191], v[214:217], v[106:109]
	s_waitcnt lgkmcnt(0)
	v_mfma_f32_16x16x32_bf16 v[102:105], v[180:183], v[222:225], v[102:105]
	v_mfma_f32_16x16x32_bf16 v[98:101], v[188:191], v[222:225], v[98:101]
	s_setprio 0
	s_barrier
	s_add_i32 s57, 0, 0x1c000
	s_add_i32 s9, s9, s39
	v_add_u32_e32 v175, s57, v173
	v_lshl_add_u64 v[244:245], v[246:247], 0, s[16:17]
	s_mov_b32 m0, s9
	ds_read_b128 v[228:231], v175
	ds_read_b128 v[236:239], v175 offset:2048
	ds_read_b128 v[232:235], v175 offset:1024
	ds_read_b128 v[240:243], v175 offset:3072
	global_load_lds_dwordx4 v[244:245], off
	v_lshl_add_u64 v[244:245], v[248:249], 0, s[16:17]
	s_add_i32 m0, s9, 0x2000
	s_nop 0
	global_load_lds_dwordx4 v[244:245], off
	s_barrier
	s_setprio 1
	s_waitcnt lgkmcnt(3)
	v_mfma_f32_16x16x32_bf16 v[94:97], v[228:231], v[192:195], v[94:97]
	s_waitcnt lgkmcnt(2)
	v_mfma_f32_16x16x32_bf16 v[90:93], v[236:239], v[192:195], v[90:93]
	v_mfma_f32_16x16x32_bf16 v[86:89], v[228:231], v[200:203], v[86:89]
	v_mfma_f32_16x16x32_bf16 v[82:85], v[236:239], v[200:203], v[82:85]
	v_mfma_f32_16x16x32_bf16 v[78:81], v[228:231], v[210:213], v[78:81]
	v_mfma_f32_16x16x32_bf16 v[74:77], v[236:239], v[210:213], v[74:77]
	v_mfma_f32_16x16x32_bf16 v[70:73], v[228:231], v[218:221], v[70:73]
	v_mfma_f32_16x16x32_bf16 v[66:69], v[236:239], v[218:221], v[66:69]
	s_waitcnt lgkmcnt(1)
	v_mfma_f32_16x16x32_bf16 v[94:97], v[232:235], v[196:199], v[94:97]
	s_waitcnt lgkmcnt(0)
	v_mfma_f32_16x16x32_bf16 v[90:93], v[240:243], v[196:199], v[90:93]
	v_mfma_f32_16x16x32_bf16 v[86:89], v[232:235], v[204:207], v[86:89]
	v_mfma_f32_16x16x32_bf16 v[82:85], v[240:243], v[204:207], v[82:85]
	v_mfma_f32_16x16x32_bf16 v[78:81], v[232:235], v[214:217], v[78:81]
	v_mfma_f32_16x16x32_bf16 v[74:77], v[240:243], v[214:217], v[74:77]
	v_mfma_f32_16x16x32_bf16 v[70:73], v[232:235], v[222:225], v[70:73]
	v_mfma_f32_16x16x32_bf16 v[66:69], v[240:243], v[222:225], v[66:69]
	s_setprio 0
	s_mov_b32 m0, s55
	v_lshl_add_u64 v[244:245], v[250:251], 0, s[16:17]
	s_barrier
	ds_read_b128 v[192:195], v174 offset:49152
	ds_read_b128 v[200:203], v174 offset:51200
	ds_read_b128 v[210:213], v174 offset:53248
	ds_read_b128 v[218:221], v174 offset:55296
	ds_read_b128 v[196:199], v174 offset:50176
	ds_read_b128 v[204:207], v174 offset:52224
	ds_read_b128 v[214:217], v174 offset:54272
	ds_read_b128 v[222:225], v174 offset:56320
	global_load_lds_dwordx4 v[244:245], off
	v_lshl_add_u64 v[244:245], v[252:253], 0, s[16:17]
	s_mov_b32 m0, s56
	s_nop 0
	global_load_lds_dwordx4 v[244:245], off
	s_barrier
	s_setprio 1
	s_waitcnt lgkmcnt(7)
	v_mfma_f32_16x16x32_bf16 v[62:65], v[176:179], v[192:195], v[62:65]
	v_mfma_f32_16x16x32_bf16 v[58:61], v[184:187], v[192:195], v[58:61]
	s_waitcnt lgkmcnt(6)
	v_mfma_f32_16x16x32_bf16 v[54:57], v[176:179], v[200:203], v[54:57]
	v_mfma_f32_16x16x32_bf16 v[50:53], v[184:187], v[200:203], v[50:53]
	s_waitcnt lgkmcnt(5)
	v_mfma_f32_16x16x32_bf16 v[46:49], v[176:179], v[210:213], v[46:49]
	v_mfma_f32_16x16x32_bf16 v[42:45], v[184:187], v[210:213], v[42:45]
	s_waitcnt lgkmcnt(4)
	v_mfma_f32_16x16x32_bf16 v[38:41], v[176:179], v[218:221], v[38:41]
	v_mfma_f32_16x16x32_bf16 v[34:37], v[184:187], v[218:221], v[34:37]
	s_waitcnt lgkmcnt(3)
	v_mfma_f32_16x16x32_bf16 v[62:65], v[180:183], v[196:199], v[62:65]
	v_mfma_f32_16x16x32_bf16 v[58:61], v[188:191], v[196:199], v[58:61]
	s_waitcnt lgkmcnt(2)
	v_mfma_f32_16x16x32_bf16 v[54:57], v[180:183], v[204:207], v[54:57]
	v_mfma_f32_16x16x32_bf16 v[50:53], v[188:191], v[204:207], v[50:53]
	s_waitcnt lgkmcnt(1)
	v_mfma_f32_16x16x32_bf16 v[46:49], v[180:183], v[214:217], v[46:49]
	v_mfma_f32_16x16x32_bf16 v[42:45], v[188:191], v[214:217], v[42:45]
	s_waitcnt lgkmcnt(0)
	v_mfma_f32_16x16x32_bf16 v[38:41], v[180:183], v[222:225], v[38:41]
	v_mfma_f32_16x16x32_bf16 v[34:37], v[188:191], v[222:225], v[34:37]
	s_setprio 0
	s_barrier
	v_lshl_add_u64 v[170:171], v[170:171], 0, s[18:19]
	s_add_i32 s9, s57, s39
	v_lshl_add_u64 v[176:177], v[170:171], 0, v[134:135]
	s_mov_b32 m0, s9
	v_lshl_add_u64 v[170:171], v[170:171], 0, v[144:145]
	global_load_lds_dwordx4 v[176:177], off
	s_add_i32 m0, s9, 0x2000
	s_nop 0
	global_load_lds_dwordx4 v[170:171], off
	s_waitcnt vmcnt(6)
	s_barrier
	s_setprio 1
	v_mfma_f32_16x16x32_bf16 v[30:33], v[228:231], v[192:195], v[30:33]
	v_mfma_f32_16x16x32_bf16 v[26:29], v[236:239], v[192:195], v[26:29]
	v_mfma_f32_16x16x32_bf16 v[22:25], v[228:231], v[200:203], v[22:25]
	v_mfma_f32_16x16x32_bf16 v[18:21], v[236:239], v[200:203], v[18:21]
	v_mfma_f32_16x16x32_bf16 v[14:17], v[228:231], v[210:213], v[14:17]
	v_mfma_f32_16x16x32_bf16 v[10:13], v[236:239], v[210:213], v[10:13]
	v_mfma_f32_16x16x32_bf16 v[6:9], v[228:231], v[218:221], v[6:9]
	v_mfma_f32_16x16x32_bf16 v[2:5], v[236:239], v[218:221], v[2:5]
	v_mfma_f32_16x16x32_bf16 v[30:33], v[232:235], v[196:199], v[30:33]
	v_mfma_f32_16x16x32_bf16 v[26:29], v[240:243], v[196:199], v[26:29]
	v_mfma_f32_16x16x32_bf16 v[22:25], v[232:235], v[204:207], v[22:25]
	v_mfma_f32_16x16x32_bf16 v[18:21], v[240:243], v[204:207], v[18:21]
	v_mfma_f32_16x16x32_bf16 v[14:17], v[232:235], v[214:217], v[14:17]
	v_mfma_f32_16x16x32_bf16 v[10:13], v[240:243], v[214:217], v[10:13]
	v_mfma_f32_16x16x32_bf16 v[6:9], v[232:235], v[222:225], v[6:9]
	v_mfma_f32_16x16x32_bf16 v[2:5], v[240:243], v[222:225], v[2:5]
	s_setprio 0
	s_add_i32 s8, s8, 2
	s_add_u32 s6, s6, 0x100
	s_addc_u32 s7, s7, 0
	s_cmp_lt_u32 s8, 14
	s_barrier
	s_cbranch_scc1 .LBB0_914
	s_waitcnt vmcnt(0)
	s_cmpk_gt_u32 s38, 0xff
	s_cbranch_scc1 .LBB0_917
	s_barrier

.LBB0_1128:
	s_add_u32 s38, s6, 0xf8cd0080
	s_addc_u32 s39, s7, -1
	s_cmp_lg_u32 s37, 40
	s_cselect_b32 s39, s39, 0
	s_cselect_b32 s38, s38, 0
	s_add_i32 s40, 0, 0x10000
	v_add_u32_e32 v164, s40, v169
	ds_read_b128 v[172:175], v164
	ds_read_b128 v[180:183], v164 offset:2048
	ds_read_b128 v[176:179], v164 offset:1024
	ds_read_b128 v[184:187], v164 offset:3072
	v_lshl_add_u64 v[240:241], v[150:151], 0, s[38:39]
	v_lshl_add_u64 v[164:165], v[148:149], 0, s[38:39]
	v_lshl_add_u64 v[222:223], v[152:153], 0, s[6:7]
	s_add_i32 m0, s28, 0xc000
	ds_read_b128 v[188:191], v170
	ds_read_b128 v[196:199], v170 offset:2048
	ds_read_b128 v[204:207], v170 offset:4096
	ds_read_b128 v[214:217], v170 offset:6144
	ds_read_b128 v[192:195], v170 offset:1024
	ds_read_b128 v[200:203], v170 offset:3072
	ds_read_b128 v[210:213], v170 offset:5120
	ds_read_b128 v[218:221], v170 offset:7168
	global_load_lds_dwordx4 v[222:223], off
	v_lshl_add_u64 v[222:223], v[162:163], 0, s[6:7]
	s_add_i32 m0, s28, 0xe000
	s_nop 0
	global_load_lds_dwordx4 v[222:223], off
	s_waitcnt lgkmcnt(8)
	s_barrier
	s_setprio 1
	s_waitcnt lgkmcnt(7)
	v_mfma_f32_16x16x32_bf16 v[126:129], v[172:175], v[188:191], v[126:129]
	v_mfma_f32_16x16x32_bf16 v[122:125], v[180:183], v[188:191], v[122:125]
	s_waitcnt lgkmcnt(6)
	v_mfma_f32_16x16x32_bf16 v[118:121], v[172:175], v[196:199], v[118:121]
	v_mfma_f32_16x16x32_bf16 v[114:117], v[180:183], v[196:199], v[114:117]
	s_waitcnt lgkmcnt(5)
	v_mfma_f32_16x16x32_bf16 v[110:113], v[172:175], v[204:207], v[110:113]
	v_mfma_f32_16x16x32_bf16 v[106:109], v[180:183], v[204:207], v[106:109]
	s_waitcnt lgkmcnt(4)
	v_mfma_f32_16x16x32_bf16 v[102:105], v[172:175], v[214:217], v[102:105]
	v_mfma_f32_16x16x32_bf16 v[98:101], v[180:183], v[214:217], v[98:101]
	s_waitcnt lgkmcnt(3)
	v_mfma_f32_16x16x32_bf16 v[126:129], v[176:179], v[192:195], v[126:129]
	v_mfma_f32_16x16x32_bf16 v[122:125], v[184:187], v[192:195], v[122:125]
	s_waitcnt lgkmcnt(2)
	v_mfma_f32_16x16x32_bf16 v[118:121], v[176:179], v[200:203], v[118:121]
	v_mfma_f32_16x16x32_bf16 v[114:117], v[184:187], v[200:203], v[114:117]
	s_waitcnt lgkmcnt(1)
	v_mfma_f32_16x16x32_bf16 v[110:113], v[176:179], v[210:213], v[110:113]
	v_mfma_f32_16x16x32_bf16 v[106:109], v[184:187], v[210:213], v[106:109]
	s_waitcnt lgkmcnt(0)
	v_mfma_f32_16x16x32_bf16 v[102:105], v[176:179], v[218:221], v[102:105]
	v_mfma_f32_16x16x32_bf16 v[98:101], v[184:187], v[218:221], v[98:101]
	s_setprio 0
	s_barrier
	s_add_i32 s38, 0, 0x14000
	s_add_i32 s39, s40, s27
	v_add_u32_e32 v171, s38, v169
	v_lshl_add_u64 v[242:243], v[164:165], 0, v[138:139]
	s_mov_b32 m0, s39
	ds_read_b128 v[222:225], v171
	ds_read_b128 v[232:235], v171 offset:2048
	ds_read_b128 v[228:231], v171 offset:1024
	ds_read_b128 v[236:239], v171 offset:3072
	global_load_lds_dwordx4 v[242:243], off
	v_lshl_add_u64 v[244:245], v[164:165], 0, v[146:147]
	s_add_i32 m0, s39, 0x2000
	s_nop 0
	global_load_lds_dwordx4 v[244:245], off
	s_barrier
	s_setprio 1
	s_waitcnt lgkmcnt(3)
	v_mfma_f32_16x16x32_bf16 v[94:97], v[222:225], v[188:191], v[94:97]
	s_waitcnt lgkmcnt(2)
	v_mfma_f32_16x16x32_bf16 v[90:93], v[232:235], v[188:191], v[90:93]
	v_mfma_f32_16x16x32_bf16 v[86:89], v[222:225], v[196:199], v[86:89]
	v_mfma_f32_16x16x32_bf16 v[82:85], v[232:235], v[196:199], v[82:85]
	v_mfma_f32_16x16x32_bf16 v[78:81], v[222:225], v[204:207], v[78:81]
	v_mfma_f32_16x16x32_bf16 v[74:77], v[232:235], v[204:207], v[74:77]
	v_mfma_f32_16x16x32_bf16 v[70:73], v[222:225], v[214:217], v[70:73]
	v_mfma_f32_16x16x32_bf16 v[66:69], v[232:235], v[214:217], v[66:69]
	s_waitcnt lgkmcnt(1)
	v_mfma_f32_16x16x32_bf16 v[94:97], v[228:231], v[192:195], v[94:97]
	s_waitcnt lgkmcnt(0)
	v_mfma_f32_16x16x32_bf16 v[90:93], v[236:239], v[192:195], v[90:93]
	v_mfma_f32_16x16x32_bf16 v[86:89], v[228:231], v[200:203], v[86:89]
	v_mfma_f32_16x16x32_bf16 v[82:85], v[236:239], v[200:203], v[82:85]
	v_mfma_f32_16x16x32_bf16 v[78:81], v[228:231], v[210:213], v[78:81]
	v_mfma_f32_16x16x32_bf16 v[74:77], v[236:239], v[210:213], v[74:77]
	v_mfma_f32_16x16x32_bf16 v[70:73], v[228:231], v[218:221], v[70:73]
	v_mfma_f32_16x16x32_bf16 v[66:69], v[236:239], v[218:221], v[66:69]
	s_setprio 0
	s_mov_b32 m0, s28
	v_lshl_add_u64 v[246:247], v[240:241], 0, v[138:139]
	s_barrier
	ds_read_b128 v[188:191], v170 offset:16384
	ds_read_b128 v[196:199], v170 offset:18432
	ds_read_b128 v[204:207], v170 offset:20480
	ds_read_b128 v[214:217], v170 offset:22528
	ds_read_b128 v[192:195], v170 offset:17408
	ds_read_b128 v[200:203], v170 offset:19456
	ds_read_b128 v[210:213], v170 offset:21504
	ds_read_b128 v[218:221], v170 offset:23552
	global_load_lds_dwordx4 v[246:247], off
	v_lshl_add_u64 v[248:249], v[240:241], 0, v[146:147]
	s_mov_b32 m0, s29
	s_nop 0
	global_load_lds_dwordx4 v[248:249], off
	s_barrier
	s_setprio 1
	s_waitcnt lgkmcnt(7)
	v_mfma_f32_16x16x32_bf16 v[62:65], v[172:175], v[188:191], v[62:65]
	v_mfma_f32_16x16x32_bf16 v[58:61], v[180:183], v[188:191], v[58:61]
	s_waitcnt lgkmcnt(6)
	v_mfma_f32_16x16x32_bf16 v[54:57], v[172:175], v[196:199], v[54:57]
	v_mfma_f32_16x16x32_bf16 v[50:53], v[180:183], v[196:199], v[50:53]
	s_waitcnt lgkmcnt(5)
	v_mfma_f32_16x16x32_bf16 v[46:49], v[172:175], v[204:207], v[46:49]
	v_mfma_f32_16x16x32_bf16 v[42:45], v[180:183], v[204:207], v[42:45]
	s_waitcnt lgkmcnt(4)
	v_mfma_f32_16x16x32_bf16 v[38:41], v[172:175], v[214:217], v[38:41]
	v_mfma_f32_16x16x32_bf16 v[34:37], v[180:183], v[214:217], v[34:37]
	s_waitcnt lgkmcnt(3)
	v_mfma_f32_16x16x32_bf16 v[62:65], v[176:179], v[192:195], v[62:65]
	v_mfma_f32_16x16x32_bf16 v[58:61], v[184:187], v[192:195], v[58:61]
	s_waitcnt lgkmcnt(2)
	v_mfma_f32_16x16x32_bf16 v[54:57], v[176:179], v[200:203], v[54:57]
	v_mfma_f32_16x16x32_bf16 v[50:53], v[184:187], v[200:203], v[50:53]
	s_waitcnt lgkmcnt(1)
	v_mfma_f32_16x16x32_bf16 v[46:49], v[176:179], v[210:213], v[46:49]
	v_mfma_f32_16x16x32_bf16 v[42:45], v[184:187], v[210:213], v[42:45]
	s_waitcnt lgkmcnt(0)
	v_mfma_f32_16x16x32_bf16 v[38:41], v[176:179], v[218:221], v[38:41]
	v_mfma_f32_16x16x32_bf16 v[34:37], v[184:187], v[218:221], v[34:37]
	s_setprio 0
	s_barrier
	v_lshl_add_u64 v[172:173], v[164:165], 0, s[16:17]
	s_add_i32 s38, s38, s27
	v_lshl_add_u64 v[174:175], v[172:173], 0, v[138:139]
	s_mov_b32 m0, s38
	v_lshl_add_u64 v[172:173], v[172:173], 0, v[146:147]
	global_load_lds_dwordx4 v[174:175], off
	s_add_i32 m0, s38, 0x2000
	s_nop 0
	global_load_lds_dwordx4 v[172:173], off
	s_waitcnt vmcnt(6)
	s_barrier
	s_setprio 1
	v_mfma_f32_16x16x32_bf16 v[30:33], v[222:225], v[188:191], v[30:33]
	v_mfma_f32_16x16x32_bf16 v[26:29], v[232:235], v[188:191], v[26:29]
	v_mfma_f32_16x16x32_bf16 v[22:25], v[222:225], v[196:199], v[22:25]
	v_mfma_f32_16x16x32_bf16 v[18:21], v[232:235], v[196:199], v[18:21]
	v_mfma_f32_16x16x32_bf16 v[14:17], v[222:225], v[204:207], v[14:17]
	v_mfma_f32_16x16x32_bf16 v[10:13], v[232:235], v[204:207], v[10:13]
	v_mfma_f32_16x16x32_bf16 v[6:9], v[222:225], v[214:217], v[6:9]
	v_mfma_f32_16x16x32_bf16 v[2:5], v[232:235], v[214:217], v[2:5]
	v_mfma_f32_16x16x32_bf16 v[30:33], v[228:231], v[192:195], v[30:33]
	v_mfma_f32_16x16x32_bf16 v[26:29], v[236:239], v[192:195], v[26:29]
	v_mfma_f32_16x16x32_bf16 v[22:25], v[228:231], v[200:203], v[22:25]
	v_mfma_f32_16x16x32_bf16 v[18:21], v[236:239], v[200:203], v[18:21]
	v_mfma_f32_16x16x32_bf16 v[14:17], v[228:231], v[210:213], v[14:17]
	v_mfma_f32_16x16x32_bf16 v[10:13], v[236:239], v[210:213], v[10:13]
	v_mfma_f32_16x16x32_bf16 v[6:9], v[228:231], v[218:221], v[6:9]
	v_mfma_f32_16x16x32_bf16 v[2:5], v[236:239], v[218:221], v[2:5]
	s_setprio 0
	s_add_i32 s38, 0, 0x18000
	v_add_u32_e32 v171, s38, v169
	s_barrier
	ds_read_b128 v[172:175], v171
	ds_read_b128 v[180:183], v171 offset:2048
	ds_read_b128 v[176:179], v171 offset:1024
	ds_read_b128 v[184:187], v171 offset:3072
	v_lshl_add_u64 v[222:223], v[240:241], 0, s[16:17]
	s_mov_b32 m0, s31
	v_lshl_add_u64 v[224:225], v[222:223], 0, v[138:139]
	ds_read_b128 v[188:191], v170 offset:32768
	ds_read_b128 v[196:199], v170 offset:34816
	ds_read_b128 v[204:207], v170 offset:36864
	ds_read_b128 v[214:217], v170 offset:38912
	ds_read_b128 v[192:195], v170 offset:33792
	ds_read_b128 v[200:203], v170 offset:35840
	ds_read_b128 v[210:213], v170 offset:37888
	ds_read_b128 v[218:221], v170 offset:39936
	global_load_lds_dwordx4 v[224:225], off
	v_lshl_add_u64 v[222:223], v[222:223], 0, v[146:147]
	s_mov_b32 m0, s34
	s_nop 0
	global_load_lds_dwordx4 v[222:223], off
	s_waitcnt lgkmcnt(8)
	s_barrier
	s_setprio 1
	s_waitcnt lgkmcnt(7)
	v_mfma_f32_16x16x32_bf16 v[126:129], v[172:175], v[188:191], v[126:129]
	v_mfma_f32_16x16x32_bf16 v[122:125], v[180:183], v[188:191], v[122:125]
	s_waitcnt lgkmcnt(6)
	v_mfma_f32_16x16x32_bf16 v[118:121], v[172:175], v[196:199], v[118:121]
	v_mfma_f32_16x16x32_bf16 v[114:117], v[180:183], v[196:199], v[114:117]
	s_waitcnt lgkmcnt(5)
	v_mfma_f32_16x16x32_bf16 v[110:113], v[172:175], v[204:207], v[110:113]
	v_mfma_f32_16x16x32_bf16 v[106:109], v[180:183], v[204:207], v[106:109]
	s_waitcnt lgkmcnt(4)
	v_mfma_f32_16x16x32_bf16 v[102:105], v[172:175], v[214:217], v[102:105]
	v_mfma_f32_16x16x32_bf16 v[98:101], v[180:183], v[214:217], v[98:101]
	s_waitcnt lgkmcnt(3)
	v_mfma_f32_16x16x32_bf16 v[126:129], v[176:179], v[192:195], v[126:129]
	v_mfma_f32_16x16x32_bf16 v[122:125], v[184:187], v[192:195], v[122:125]
	s_waitcnt lgkmcnt(2)
	v_mfma_f32_16x16x32_bf16 v[118:121], v[176:179], v[200:203], v[118:121]
	v_mfma_f32_16x16x32_bf16 v[114:117], v[184:187], v[200:203], v[114:117]
	s_waitcnt lgkmcnt(1)
	v_mfma_f32_16x16x32_bf16 v[110:113], v[176:179], v[210:213], v[110:113]
	v_mfma_f32_16x16x32_bf16 v[106:109], v[184:187], v[210:213], v[106:109]
	s_waitcnt lgkmcnt(0)
	v_mfma_f32_16x16x32_bf16 v[102:105], v[176:179], v[218:221], v[102:105]
	v_mfma_f32_16x16x32_bf16 v[98:101], v[184:187], v[218:221], v[98:101]
	s_setprio 0
	s_barrier
	s_add_i32 s39, 0, 0x1c000
	s_add_i32 s38, s38, s27
	v_add_u32_e32 v171, s39, v169
	v_lshl_add_u64 v[240:241], v[242:243], 0, s[18:19]
	s_mov_b32 m0, s38
	ds_read_b128 v[222:225], v171
	ds_read_b128 v[232:235], v171 offset:2048
	ds_read_b128 v[228:231], v171 offset:1024
	ds_read_b128 v[236:239], v171 offset:3072
	global_load_lds_dwordx4 v[240:241], off
	v_lshl_add_u64 v[240:241], v[244:245], 0, s[18:19]
	s_add_i32 m0, s38, 0x2000
	s_nop 0
	global_load_lds_dwordx4 v[240:241], off
	s_barrier
	s_setprio 1
	s_waitcnt lgkmcnt(3)
	v_mfma_f32_16x16x32_bf16 v[94:97], v[222:225], v[188:191], v[94:97]
	s_waitcnt lgkmcnt(2)
	v_mfma_f32_16x16x32_bf16 v[90:93], v[232:235], v[188:191], v[90:93]
	v_mfma_f32_16x16x32_bf16 v[86:89], v[222:225], v[196:199], v[86:89]
	v_mfma_f32_16x16x32_bf16 v[82:85], v[232:235], v[196:199], v[82:85]
	v_mfma_f32_16x16x32_bf16 v[78:81], v[222:225], v[204:207], v[78:81]
	v_mfma_f32_16x16x32_bf16 v[74:77], v[232:235], v[204:207], v[74:77]
	v_mfma_f32_16x16x32_bf16 v[70:73], v[222:225], v[214:217], v[70:73]
	v_mfma_f32_16x16x32_bf16 v[66:69], v[232:235], v[214:217], v[66:69]
	s_waitcnt lgkmcnt(1)
	v_mfma_f32_16x16x32_bf16 v[94:97], v[228:231], v[192:195], v[94:97]
	s_waitcnt lgkmcnt(0)
	v_mfma_f32_16x16x32_bf16 v[90:93], v[236:239], v[192:195], v[90:93]
	v_mfma_f32_16x16x32_bf16 v[86:89], v[228:231], v[200:203], v[86:89]
	v_mfma_f32_16x16x32_bf16 v[82:85], v[236:239], v[200:203], v[82:85]
	v_mfma_f32_16x16x32_bf16 v[78:81], v[228:231], v[210:213], v[78:81]
	v_mfma_f32_16x16x32_bf16 v[74:77], v[236:239], v[210:213], v[74:77]
	v_mfma_f32_16x16x32_bf16 v[70:73], v[228:231], v[218:221], v[70:73]
	v_mfma_f32_16x16x32_bf16 v[66:69], v[236:239], v[218:221], v[66:69]
	s_setprio 0
	s_mov_b32 m0, s35
	v_lshl_add_u64 v[240:241], v[246:247], 0, s[18:19]
	s_barrier
	ds_read_b128 v[188:191], v170 offset:49152
	ds_read_b128 v[196:199], v170 offset:51200
	ds_read_b128 v[204:207], v170 offset:53248
	ds_read_b128 v[214:217], v170 offset:55296
	ds_read_b128 v[192:195], v170 offset:50176
	ds_read_b128 v[200:203], v170 offset:52224
	ds_read_b128 v[210:213], v170 offset:54272
	ds_read_b128 v[218:221], v170 offset:56320
	global_load_lds_dwordx4 v[240:241], off
	v_lshl_add_u64 v[240:241], v[248:249], 0, s[18:19]
	s_mov_b32 m0, s36
	s_nop 0
	global_load_lds_dwordx4 v[240:241], off
	s_barrier
	s_setprio 1
	s_waitcnt lgkmcnt(7)
	v_mfma_f32_16x16x32_bf16 v[62:65], v[172:175], v[188:191], v[62:65]
	v_mfma_f32_16x16x32_bf16 v[58:61], v[180:183], v[188:191], v[58:61]
	s_waitcnt lgkmcnt(6)
	v_mfma_f32_16x16x32_bf16 v[54:57], v[172:175], v[196:199], v[54:57]
	v_mfma_f32_16x16x32_bf16 v[50:53], v[180:183], v[196:199], v[50:53]
	s_waitcnt lgkmcnt(5)
	v_mfma_f32_16x16x32_bf16 v[46:49], v[172:175], v[204:207], v[46:49]
	v_mfma_f32_16x16x32_bf16 v[42:45], v[180:183], v[204:207], v[42:45]
	s_waitcnt lgkmcnt(4)
	v_mfma_f32_16x16x32_bf16 v[38:41], v[172:175], v[214:217], v[38:41]
	v_mfma_f32_16x16x32_bf16 v[34:37], v[180:183], v[214:217], v[34:37]
	s_waitcnt lgkmcnt(3)
	v_mfma_f32_16x16x32_bf16 v[62:65], v[176:179], v[192:195], v[62:65]
	v_mfma_f32_16x16x32_bf16 v[58:61], v[184:187], v[192:195], v[58:61]
	s_waitcnt lgkmcnt(2)
	v_mfma_f32_16x16x32_bf16 v[54:57], v[176:179], v[200:203], v[54:57]
	v_mfma_f32_16x16x32_bf16 v[50:53], v[184:187], v[200:203], v[50:53]
	s_waitcnt lgkmcnt(1)
	v_mfma_f32_16x16x32_bf16 v[46:49], v[176:179], v[210:213], v[46:49]
	v_mfma_f32_16x16x32_bf16 v[42:45], v[184:187], v[210:213], v[42:45]
	s_waitcnt lgkmcnt(0)
	v_mfma_f32_16x16x32_bf16 v[38:41], v[176:179], v[218:221], v[38:41]
	v_mfma_f32_16x16x32_bf16 v[34:37], v[184:187], v[218:221], v[34:37]
	s_setprio 0
	s_barrier
	v_lshl_add_u64 v[164:165], v[164:165], 0, s[20:21]
	s_add_i32 s38, s39, s27
	v_lshl_add_u64 v[172:173], v[164:165], 0, v[138:139]
	s_mov_b32 m0, s38
	v_lshl_add_u64 v[164:165], v[164:165], 0, v[146:147]
	global_load_lds_dwordx4 v[172:173], off
	s_add_i32 m0, s38, 0x2000
	s_nop 0
	global_load_lds_dwordx4 v[164:165], off
	s_waitcnt vmcnt(6)
	s_barrier
	s_setprio 1
	v_mfma_f32_16x16x32_bf16 v[30:33], v[222:225], v[188:191], v[30:33]
	v_mfma_f32_16x16x32_bf16 v[26:29], v[232:235], v[188:191], v[26:29]
	v_mfma_f32_16x16x32_bf16 v[22:25], v[222:225], v[196:199], v[22:25]
	v_mfma_f32_16x16x32_bf16 v[18:21], v[232:235], v[196:199], v[18:21]
	v_mfma_f32_16x16x32_bf16 v[14:17], v[222:225], v[204:207], v[14:17]
	v_mfma_f32_16x16x32_bf16 v[10:13], v[232:235], v[204:207], v[10:13]
	v_mfma_f32_16x16x32_bf16 v[6:9], v[222:225], v[214:217], v[6:9]
	v_mfma_f32_16x16x32_bf16 v[2:5], v[232:235], v[214:217], v[2:5]
	v_mfma_f32_16x16x32_bf16 v[30:33], v[228:231], v[192:195], v[30:33]
	v_mfma_f32_16x16x32_bf16 v[26:29], v[236:239], v[192:195], v[26:29]
	v_mfma_f32_16x16x32_bf16 v[22:25], v[228:231], v[200:203], v[22:25]
	v_mfma_f32_16x16x32_bf16 v[18:21], v[236:239], v[200:203], v[18:21]
	v_mfma_f32_16x16x32_bf16 v[14:17], v[228:231], v[210:213], v[14:17]
	v_mfma_f32_16x16x32_bf16 v[10:13], v[236:239], v[210:213], v[10:13]
	v_mfma_f32_16x16x32_bf16 v[6:9], v[228:231], v[218:221], v[6:9]
	v_mfma_f32_16x16x32_bf16 v[2:5], v[236:239], v[218:221], v[2:5]
	s_setprio 0
	s_add_i32 s37, s37, 2
	s_add_u32 s6, s6, 0x100
	s_addc_u32 s7, s7, 0
	s_cmp_lt_u32 s37, 42
	s_barrier
	s_cbranch_scc1 .LBB0_1128
	s_waitcnt vmcnt(0)
	s_cmpk_gt_u32 s26, 0xff
	s_cbranch_scc1 .LBB0_1131
	s_barrier

.LBB0_1271:
	s_cmpk_eq_i32 s6, 0x700
	v_lshl_add_u64 v[170:171], v[162:163], 0, s[6:7]
	v_lshl_add_u64 v[170:171], v[170:171], 0, s[18:19]
	s_cselect_b64 vcc, -1, 0
	s_add_i32 s25, 0, 0x10000
	v_cndmask_b32_e32 v245, v171, v153, vcc
	v_add_u32_e32 v171, s25, v173
	ds_read_b128 v[176:179], v171
	ds_read_b128 v[184:187], v171 offset:2048
	ds_read_b128 v[180:183], v171 offset:1024
	ds_read_b128 v[188:191], v171 offset:3072
	v_cndmask_b32_e32 v244, v170, v152, vcc
	v_lshl_add_u64 v[170:171], v[168:169], 0, s[6:7]
	v_cndmask_b32_e32 v171, v171, v151, vcc
	v_cndmask_b32_e32 v170, v170, v150, vcc
	v_lshl_add_u64 v[228:229], v[164:165], 0, s[6:7]
	s_add_i32 m0, s20, 0xc000
	ds_read_b128 v[192:195], v174
	ds_read_b128 v[200:203], v174 offset:2048
	ds_read_b128 v[210:213], v174 offset:4096
	ds_read_b128 v[218:221], v174 offset:6144
	ds_read_b128 v[196:199], v174 offset:1024
	ds_read_b128 v[204:207], v174 offset:3072
	ds_read_b128 v[214:217], v174 offset:5120
	ds_read_b128 v[222:225], v174 offset:7168
	global_load_lds_dwordx4 v[228:229], off
	v_lshl_add_u64 v[228:229], v[166:167], 0, s[6:7]
	s_add_i32 m0, s20, 0xe000
	s_nop 0
	global_load_lds_dwordx4 v[228:229], off
	s_waitcnt lgkmcnt(8)
	s_barrier
	s_setprio 1
	s_waitcnt lgkmcnt(7)
	v_mfma_f32_16x16x32_bf16 v[126:129], v[176:179], v[192:195], v[126:129]
	v_mfma_f32_16x16x32_bf16 v[122:125], v[184:187], v[192:195], v[122:125]
	s_waitcnt lgkmcnt(6)
	v_mfma_f32_16x16x32_bf16 v[118:121], v[176:179], v[200:203], v[118:121]
	v_mfma_f32_16x16x32_bf16 v[114:117], v[184:187], v[200:203], v[114:117]
	s_waitcnt lgkmcnt(5)
	v_mfma_f32_16x16x32_bf16 v[110:113], v[176:179], v[210:213], v[110:113]
	v_mfma_f32_16x16x32_bf16 v[106:109], v[184:187], v[210:213], v[106:109]
	s_waitcnt lgkmcnt(4)
	v_mfma_f32_16x16x32_bf16 v[102:105], v[176:179], v[218:221], v[102:105]
	v_mfma_f32_16x16x32_bf16 v[98:101], v[184:187], v[218:221], v[98:101]
	s_waitcnt lgkmcnt(3)
	v_mfma_f32_16x16x32_bf16 v[126:129], v[180:183], v[196:199], v[126:129]
	v_mfma_f32_16x16x32_bf16 v[122:125], v[188:191], v[196:199], v[122:125]
	s_waitcnt lgkmcnt(2)
	v_mfma_f32_16x16x32_bf16 v[118:121], v[180:183], v[204:207], v[118:121]
	v_mfma_f32_16x16x32_bf16 v[114:117], v[188:191], v[204:207], v[114:117]
	s_waitcnt lgkmcnt(1)
	v_mfma_f32_16x16x32_bf16 v[110:113], v[180:183], v[214:217], v[110:113]
	v_mfma_f32_16x16x32_bf16 v[106:109], v[188:191], v[214:217], v[106:109]
	s_waitcnt lgkmcnt(0)
	v_mfma_f32_16x16x32_bf16 v[102:105], v[180:183], v[222:225], v[102:105]
	v_mfma_f32_16x16x32_bf16 v[98:101], v[188:191], v[222:225], v[98:101]
	s_setprio 0
	s_barrier
	s_add_i32 s41, 0, 0x14000
	s_add_i32 s25, s25, s35
	v_add_u32_e32 v175, s41, v173
	v_lshl_add_u64 v[246:247], v[170:171], 0, v[138:139]
	s_mov_b32 m0, s25
	ds_read_b128 v[228:231], v175
	ds_read_b128 v[236:239], v175 offset:2048
	ds_read_b128 v[232:235], v175 offset:1024
	ds_read_b128 v[240:243], v175 offset:3072
	global_load_lds_dwordx4 v[246:247], off
	v_lshl_add_u64 v[248:249], v[170:171], 0, v[148:149]
	s_add_i32 m0, s25, 0x2000
	s_nop 0
	global_load_lds_dwordx4 v[248:249], off
	s_barrier
	s_setprio 1
	s_waitcnt lgkmcnt(3)
	v_mfma_f32_16x16x32_bf16 v[94:97], v[228:231], v[192:195], v[94:97]
	s_waitcnt lgkmcnt(2)
	v_mfma_f32_16x16x32_bf16 v[90:93], v[236:239], v[192:195], v[90:93]
	v_mfma_f32_16x16x32_bf16 v[86:89], v[228:231], v[200:203], v[86:89]
	v_mfma_f32_16x16x32_bf16 v[82:85], v[236:239], v[200:203], v[82:85]
	v_mfma_f32_16x16x32_bf16 v[78:81], v[228:231], v[210:213], v[78:81]
	v_mfma_f32_16x16x32_bf16 v[74:77], v[236:239], v[210:213], v[74:77]
	v_mfma_f32_16x16x32_bf16 v[70:73], v[228:231], v[218:221], v[70:73]
	v_mfma_f32_16x16x32_bf16 v[66:69], v[236:239], v[218:221], v[66:69]
	s_waitcnt lgkmcnt(1)
	v_mfma_f32_16x16x32_bf16 v[94:97], v[232:235], v[196:199], v[94:97]
	s_waitcnt lgkmcnt(0)
	v_mfma_f32_16x16x32_bf16 v[90:93], v[240:243], v[196:199], v[90:93]
	v_mfma_f32_16x16x32_bf16 v[86:89], v[232:235], v[204:207], v[86:89]
	v_mfma_f32_16x16x32_bf16 v[82:85], v[240:243], v[204:207], v[82:85]
	v_mfma_f32_16x16x32_bf16 v[78:81], v[232:235], v[214:217], v[78:81]
	v_mfma_f32_16x16x32_bf16 v[74:77], v[240:243], v[214:217], v[74:77]
	v_mfma_f32_16x16x32_bf16 v[70:73], v[232:235], v[222:225], v[70:73]
	v_mfma_f32_16x16x32_bf16 v[66:69], v[240:243], v[222:225], v[66:69]
	s_setprio 0
	s_mov_b32 m0, s20
	v_lshl_add_u64 v[250:251], v[244:245], 0, v[138:139]
	s_barrier
	ds_read_b128 v[192:195], v174 offset:16384
	ds_read_b128 v[200:203], v174 offset:18432
	ds_read_b128 v[210:213], v174 offset:20480
	ds_read_b128 v[218:221], v174 offset:22528
	ds_read_b128 v[196:199], v174 offset:17408
	ds_read_b128 v[204:207], v174 offset:19456
	ds_read_b128 v[214:217], v174 offset:21504
	ds_read_b128 v[222:225], v174 offset:23552
	global_load_lds_dwordx4 v[250:251], off
	v_lshl_add_u64 v[252:253], v[244:245], 0, v[148:149]
	s_mov_b32 m0, s36
	s_nop 0
	global_load_lds_dwordx4 v[252:253], off
	s_barrier
	s_setprio 1
	s_waitcnt lgkmcnt(7)
	v_mfma_f32_16x16x32_bf16 v[62:65], v[176:179], v[192:195], v[62:65]
	v_mfma_f32_16x16x32_bf16 v[58:61], v[184:187], v[192:195], v[58:61]
	s_waitcnt lgkmcnt(6)
	v_mfma_f32_16x16x32_bf16 v[54:57], v[176:179], v[200:203], v[54:57]
	v_mfma_f32_16x16x32_bf16 v[50:53], v[184:187], v[200:203], v[50:53]
	s_waitcnt lgkmcnt(5)
	v_mfma_f32_16x16x32_bf16 v[46:49], v[176:179], v[210:213], v[46:49]
	v_mfma_f32_16x16x32_bf16 v[42:45], v[184:187], v[210:213], v[42:45]
	s_waitcnt lgkmcnt(4)
	v_mfma_f32_16x16x32_bf16 v[38:41], v[176:179], v[218:221], v[38:41]
	v_mfma_f32_16x16x32_bf16 v[34:37], v[184:187], v[218:221], v[34:37]
	s_waitcnt lgkmcnt(3)
	v_mfma_f32_16x16x32_bf16 v[62:65], v[180:183], v[196:199], v[62:65]
	v_mfma_f32_16x16x32_bf16 v[58:61], v[188:191], v[196:199], v[58:61]
	s_waitcnt lgkmcnt(2)
	v_mfma_f32_16x16x32_bf16 v[54:57], v[180:183], v[204:207], v[54:57]
	v_mfma_f32_16x16x32_bf16 v[50:53], v[188:191], v[204:207], v[50:53]
	s_waitcnt lgkmcnt(1)
	v_mfma_f32_16x16x32_bf16 v[46:49], v[180:183], v[214:217], v[46:49]
	v_mfma_f32_16x16x32_bf16 v[42:45], v[188:191], v[214:217], v[42:45]
	s_waitcnt lgkmcnt(0)
	v_mfma_f32_16x16x32_bf16 v[38:41], v[180:183], v[222:225], v[38:41]
	v_mfma_f32_16x16x32_bf16 v[34:37], v[188:191], v[222:225], v[34:37]
	s_setprio 0
	s_barrier
	v_lshl_add_u64 v[176:177], v[170:171], 0, s[12:13]
	s_add_i32 s25, s41, s35
	v_lshl_add_u64 v[178:179], v[176:177], 0, v[138:139]
	s_mov_b32 m0, s25
	v_lshl_add_u64 v[176:177], v[176:177], 0, v[148:149]
	global_load_lds_dwordx4 v[178:179], off
	s_add_i32 m0, s25, 0x2000
	s_nop 0
	global_load_lds_dwordx4 v[176:177], off
	s_waitcnt vmcnt(6)
	s_barrier
	s_setprio 1
	v_mfma_f32_16x16x32_bf16 v[30:33], v[228:231], v[192:195], v[30:33]
	v_mfma_f32_16x16x32_bf16 v[26:29], v[236:239], v[192:195], v[26:29]
	v_mfma_f32_16x16x32_bf16 v[22:25], v[228:231], v[200:203], v[22:25]
	v_mfma_f32_16x16x32_bf16 v[18:21], v[236:239], v[200:203], v[18:21]
	v_mfma_f32_16x16x32_bf16 v[14:17], v[228:231], v[210:213], v[14:17]
	v_mfma_f32_16x16x32_bf16 v[10:13], v[236:239], v[210:213], v[10:13]
	v_mfma_f32_16x16x32_bf16 v[6:9], v[228:231], v[218:221], v[6:9]
	v_mfma_f32_16x16x32_bf16 v[2:5], v[236:239], v[218:221], v[2:5]
	v_mfma_f32_16x16x32_bf16 v[30:33], v[232:235], v[196:199], v[30:33]
	v_mfma_f32_16x16x32_bf16 v[26:29], v[240:243], v[196:199], v[26:29]
	v_mfma_f32_16x16x32_bf16 v[22:25], v[232:235], v[204:207], v[22:25]
	v_mfma_f32_16x16x32_bf16 v[18:21], v[240:243], v[204:207], v[18:21]
	v_mfma_f32_16x16x32_bf16 v[14:17], v[232:235], v[214:217], v[14:17]
	v_mfma_f32_16x16x32_bf16 v[10:13], v[240:243], v[214:217], v[10:13]
	v_mfma_f32_16x16x32_bf16 v[6:9], v[232:235], v[222:225], v[6:9]
	v_mfma_f32_16x16x32_bf16 v[2:5], v[240:243], v[222:225], v[2:5]
	s_setprio 0
	s_add_i32 s25, 0, 0x18000
	v_add_u32_e32 v175, s25, v173
	s_barrier
	ds_read_b128 v[176:179], v175
	ds_read_b128 v[184:187], v175 offset:2048
	ds_read_b128 v[180:183], v175 offset:1024
	ds_read_b128 v[188:191], v175 offset:3072
	v_lshl_add_u64 v[228:229], v[244:245], 0, s[12:13]
	s_mov_b32 m0, s37
	v_lshl_add_u64 v[230:231], v[228:229], 0, v[138:139]
	ds_read_b128 v[192:195], v174 offset:32768
	ds_read_b128 v[200:203], v174 offset:34816
	ds_read_b128 v[210:213], v174 offset:36864
	ds_read_b128 v[218:221], v174 offset:38912
	ds_read_b128 v[196:199], v174 offset:33792
	ds_read_b128 v[204:207], v174 offset:35840
	ds_read_b128 v[214:217], v174 offset:37888
	ds_read_b128 v[222:225], v174 offset:39936
	global_load_lds_dwordx4 v[230:231], off
	v_lshl_add_u64 v[228:229], v[228:229], 0, v[148:149]
	s_mov_b32 m0, s38
	s_nop 0
	global_load_lds_dwordx4 v[228:229], off
	s_waitcnt lgkmcnt(8)
	s_barrier
	s_setprio 1
	s_waitcnt lgkmcnt(7)
	v_mfma_f32_16x16x32_bf16 v[126:129], v[176:179], v[192:195], v[126:129]
	v_mfma_f32_16x16x32_bf16 v[122:125], v[184:187], v[192:195], v[122:125]
	s_waitcnt lgkmcnt(6)
	v_mfma_f32_16x16x32_bf16 v[118:121], v[176:179], v[200:203], v[118:121]
	v_mfma_f32_16x16x32_bf16 v[114:117], v[184:187], v[200:203], v[114:117]
	s_waitcnt lgkmcnt(5)
	v_mfma_f32_16x16x32_bf16 v[110:113], v[176:179], v[210:213], v[110:113]
	v_mfma_f32_16x16x32_bf16 v[106:109], v[184:187], v[210:213], v[106:109]
	s_waitcnt lgkmcnt(4)
	v_mfma_f32_16x16x32_bf16 v[102:105], v[176:179], v[218:221], v[102:105]
	v_mfma_f32_16x16x32_bf16 v[98:101], v[184:187], v[218:221], v[98:101]
	s_waitcnt lgkmcnt(3)
	v_mfma_f32_16x16x32_bf16 v[126:129], v[180:183], v[196:199], v[126:129]
	v_mfma_f32_16x16x32_bf16 v[122:125], v[188:191], v[196:199], v[122:125]
	s_waitcnt lgkmcnt(2)
	v_mfma_f32_16x16x32_bf16 v[118:121], v[180:183], v[204:207], v[118:121]
	v_mfma_f32_16x16x32_bf16 v[114:117], v[188:191], v[204:207], v[114:117]
	s_waitcnt lgkmcnt(1)
	v_mfma_f32_16x16x32_bf16 v[110:113], v[180:183], v[214:217], v[110:113]
	v_mfma_f32_16x16x32_bf16 v[106:109], v[188:191], v[214:217], v[106:109]
	s_waitcnt lgkmcnt(0)
	v_mfma_f32_16x16x32_bf16 v[102:105], v[180:183], v[222:225], v[102:105]
	v_mfma_f32_16x16x32_bf16 v[98:101], v[188:191], v[222:225], v[98:101]
	s_setprio 0
	s_barrier
	s_add_i32 s41, 0, 0x1c000
	s_add_i32 s25, s25, s35
	v_add_u32_e32 v175, s41, v173
	v_lshl_add_u64 v[244:245], v[246:247], 0, s[14:15]
	s_mov_b32 m0, s25
	ds_read_b128 v[228:231], v175
	ds_read_b128 v[236:239], v175 offset:2048
	ds_read_b128 v[232:235], v175 offset:1024
	ds_read_b128 v[240:243], v175 offset:3072
	global_load_lds_dwordx4 v[244:245], off
	v_lshl_add_u64 v[244:245], v[248:249], 0, s[14:15]
	s_add_i32 m0, s25, 0x2000
	s_nop 0
	global_load_lds_dwordx4 v[244:245], off
	s_barrier
	s_setprio 1
	s_waitcnt lgkmcnt(3)
	v_mfma_f32_16x16x32_bf16 v[94:97], v[228:231], v[192:195], v[94:97]
	s_waitcnt lgkmcnt(2)
	v_mfma_f32_16x16x32_bf16 v[90:93], v[236:239], v[192:195], v[90:93]
	v_mfma_f32_16x16x32_bf16 v[86:89], v[228:231], v[200:203], v[86:89]
	v_mfma_f32_16x16x32_bf16 v[82:85], v[236:239], v[200:203], v[82:85]
	v_mfma_f32_16x16x32_bf16 v[78:81], v[228:231], v[210:213], v[78:81]
	v_mfma_f32_16x16x32_bf16 v[74:77], v[236:239], v[210:213], v[74:77]
	v_mfma_f32_16x16x32_bf16 v[70:73], v[228:231], v[218:221], v[70:73]
	v_mfma_f32_16x16x32_bf16 v[66:69], v[236:239], v[218:221], v[66:69]
	s_waitcnt lgkmcnt(1)
	v_mfma_f32_16x16x32_bf16 v[94:97], v[232:235], v[196:199], v[94:97]
	s_waitcnt lgkmcnt(0)
	v_mfma_f32_16x16x32_bf16 v[90:93], v[240:243], v[196:199], v[90:93]
	v_mfma_f32_16x16x32_bf16 v[86:89], v[232:235], v[204:207], v[86:89]
	v_mfma_f32_16x16x32_bf16 v[82:85], v[240:243], v[204:207], v[82:85]
	v_mfma_f32_16x16x32_bf16 v[78:81], v[232:235], v[214:217], v[78:81]
	v_mfma_f32_16x16x32_bf16 v[74:77], v[240:243], v[214:217], v[74:77]
	v_mfma_f32_16x16x32_bf16 v[70:73], v[232:235], v[222:225], v[70:73]
	v_mfma_f32_16x16x32_bf16 v[66:69], v[240:243], v[222:225], v[66:69]
	s_setprio 0
	s_mov_b32 m0, s39
	v_lshl_add_u64 v[244:245], v[250:251], 0, s[14:15]
	s_barrier
	ds_read_b128 v[192:195], v174 offset:49152
	ds_read_b128 v[200:203], v174 offset:51200
	ds_read_b128 v[210:213], v174 offset:53248
	ds_read_b128 v[218:221], v174 offset:55296
	ds_read_b128 v[196:199], v174 offset:50176
	ds_read_b128 v[204:207], v174 offset:52224
	ds_read_b128 v[214:217], v174 offset:54272
	ds_read_b128 v[222:225], v174 offset:56320
	global_load_lds_dwordx4 v[244:245], off
	v_lshl_add_u64 v[244:245], v[252:253], 0, s[14:15]
	s_mov_b32 m0, s40
	s_nop 0
	global_load_lds_dwordx4 v[244:245], off
	s_barrier
	s_setprio 1
	s_waitcnt lgkmcnt(7)
	v_mfma_f32_16x16x32_bf16 v[62:65], v[176:179], v[192:195], v[62:65]
	v_mfma_f32_16x16x32_bf16 v[58:61], v[184:187], v[192:195], v[58:61]
	s_waitcnt lgkmcnt(6)
	v_mfma_f32_16x16x32_bf16 v[54:57], v[176:179], v[200:203], v[54:57]
	v_mfma_f32_16x16x32_bf16 v[50:53], v[184:187], v[200:203], v[50:53]
	s_waitcnt lgkmcnt(5)
	v_mfma_f32_16x16x32_bf16 v[46:49], v[176:179], v[210:213], v[46:49]
	v_mfma_f32_16x16x32_bf16 v[42:45], v[184:187], v[210:213], v[42:45]
	s_waitcnt lgkmcnt(4)
	v_mfma_f32_16x16x32_bf16 v[38:41], v[176:179], v[218:221], v[38:41]
	v_mfma_f32_16x16x32_bf16 v[34:37], v[184:187], v[218:221], v[34:37]
	s_waitcnt lgkmcnt(3)
	v_mfma_f32_16x16x32_bf16 v[62:65], v[180:183], v[196:199], v[62:65]
	v_mfma_f32_16x16x32_bf16 v[58:61], v[188:191], v[196:199], v[58:61]
	s_waitcnt lgkmcnt(2)
	v_mfma_f32_16x16x32_bf16 v[54:57], v[180:183], v[204:207], v[54:57]
	v_mfma_f32_16x16x32_bf16 v[50:53], v[188:191], v[204:207], v[50:53]
	s_waitcnt lgkmcnt(1)
	v_mfma_f32_16x16x32_bf16 v[46:49], v[180:183], v[214:217], v[46:49]
	v_mfma_f32_16x16x32_bf16 v[42:45], v[188:191], v[214:217], v[42:45]
	s_waitcnt lgkmcnt(0)
	v_mfma_f32_16x16x32_bf16 v[38:41], v[180:183], v[222:225], v[38:41]
	v_mfma_f32_16x16x32_bf16 v[34:37], v[188:191], v[222:225], v[34:37]
	s_setprio 0
	s_barrier
	v_lshl_add_u64 v[170:171], v[170:171], 0, s[16:17]
	s_add_i32 s25, s41, s35
	v_lshl_add_u64 v[176:177], v[170:171], 0, v[138:139]
	s_mov_b32 m0, s25
	v_lshl_add_u64 v[170:171], v[170:171], 0, v[148:149]
	global_load_lds_dwordx4 v[176:177], off
	s_add_i32 m0, s25, 0x2000
	s_nop 0
	global_load_lds_dwordx4 v[170:171], off
	s_waitcnt vmcnt(6)
	s_barrier
	s_setprio 1
	v_mfma_f32_16x16x32_bf16 v[30:33], v[228:231], v[192:195], v[30:33]
	v_mfma_f32_16x16x32_bf16 v[26:29], v[236:239], v[192:195], v[26:29]
	v_mfma_f32_16x16x32_bf16 v[22:25], v[228:231], v[200:203], v[22:25]
	v_mfma_f32_16x16x32_bf16 v[18:21], v[236:239], v[200:203], v[18:21]
	v_mfma_f32_16x16x32_bf16 v[14:17], v[228:231], v[210:213], v[14:17]
	v_mfma_f32_16x16x32_bf16 v[10:13], v[236:239], v[210:213], v[10:13]
	v_mfma_f32_16x16x32_bf16 v[6:9], v[228:231], v[218:221], v[6:9]
	v_mfma_f32_16x16x32_bf16 v[2:5], v[236:239], v[218:221], v[2:5]
	v_mfma_f32_16x16x32_bf16 v[30:33], v[232:235], v[196:199], v[30:33]
	v_mfma_f32_16x16x32_bf16 v[26:29], v[240:243], v[196:199], v[26:29]
	v_mfma_f32_16x16x32_bf16 v[22:25], v[232:235], v[204:207], v[22:25]
	v_mfma_f32_16x16x32_bf16 v[18:21], v[240:243], v[204:207], v[18:21]
	v_mfma_f32_16x16x32_bf16 v[14:17], v[232:235], v[214:217], v[14:17]
	v_mfma_f32_16x16x32_bf16 v[10:13], v[240:243], v[214:217], v[10:13]
	v_mfma_f32_16x16x32_bf16 v[6:9], v[232:235], v[222:225], v[6:9]
	v_mfma_f32_16x16x32_bf16 v[2:5], v[240:243], v[222:225], v[2:5]
	s_setprio 0
	s_add_i32 s24, s24, 2
	s_add_u32 s6, s6, 0x100
	s_addc_u32 s7, s7, 0
	s_cmp_lt_u32 s24, 14
	s_barrier
	s_cbranch_scc1 .LBB0_1271
	s_waitcnt vmcnt(0)
	s_cmpk_gt_u32 s27, 0xff
	s_cbranch_scc1 .LBB0_1274
	s_barrier

.LBB0_1645:
	s_add_u32 s33, s6, 0xfbd40080
	s_addc_u32 s34, s7, -1
	s_cmp_lg_u32 s31, 12
	s_cselect_b32 s35, s34, 0
	s_cselect_b32 s34, s33, 0
	s_add_i32 s33, 0, 0x10000
	v_add_u32_e32 v164, s33, v167
	ds_read_b128 v[170:173], v164
	ds_read_b128 v[178:181], v164 offset:2048
	ds_read_b128 v[174:177], v164 offset:1024
	ds_read_b128 v[182:185], v164 offset:3072
	v_lshl_add_u64 v[206:207], v[150:151], 0, s[34:35]
	v_lshl_add_u64 v[164:165], v[148:149], 0, s[34:35]
	v_lshl_add_u64 v[222:223], v[152:153], 0, s[6:7]
	s_add_i32 m0, s17, 0xc000
	ds_read_b128 v[186:189], v168
	ds_read_b128 v[194:197], v168 offset:2048
	ds_read_b128 v[202:205], v168 offset:4096
	ds_read_b128 v[214:217], v168 offset:6144
	ds_read_b128 v[190:193], v168 offset:1024
	ds_read_b128 v[198:201], v168 offset:3072
	ds_read_b128 v[210:213], v168 offset:5120
	ds_read_b128 v[218:221], v168 offset:7168
	global_load_lds_dwordx4 v[222:223], off
	v_lshl_add_u64 v[222:223], v[162:163], 0, s[6:7]
	s_add_i32 m0, s17, 0xe000
	s_nop 0
	global_load_lds_dwordx4 v[222:223], off
	s_waitcnt lgkmcnt(8)
	s_barrier
	s_setprio 1
	s_waitcnt lgkmcnt(7)
	v_mfma_f32_16x16x32_bf16 v[126:129], v[170:173], v[186:189], v[126:129]
	v_mfma_f32_16x16x32_bf16 v[122:125], v[178:181], v[186:189], v[122:125]
	s_waitcnt lgkmcnt(6)
	v_mfma_f32_16x16x32_bf16 v[118:121], v[170:173], v[194:197], v[118:121]
	v_mfma_f32_16x16x32_bf16 v[114:117], v[178:181], v[194:197], v[114:117]
	s_waitcnt lgkmcnt(5)
	v_mfma_f32_16x16x32_bf16 v[110:113], v[170:173], v[202:205], v[110:113]
	v_mfma_f32_16x16x32_bf16 v[106:109], v[178:181], v[202:205], v[106:109]
	s_waitcnt lgkmcnt(4)
	v_mfma_f32_16x16x32_bf16 v[102:105], v[170:173], v[214:217], v[102:105]
	v_mfma_f32_16x16x32_bf16 v[98:101], v[178:181], v[214:217], v[98:101]
	s_waitcnt lgkmcnt(3)
	v_mfma_f32_16x16x32_bf16 v[126:129], v[174:177], v[190:193], v[126:129]
	v_mfma_f32_16x16x32_bf16 v[122:125], v[182:185], v[190:193], v[122:125]
	s_waitcnt lgkmcnt(2)
	v_mfma_f32_16x16x32_bf16 v[118:121], v[174:177], v[198:201], v[118:121]
	v_mfma_f32_16x16x32_bf16 v[114:117], v[182:185], v[198:201], v[114:117]
	s_waitcnt lgkmcnt(1)
	v_mfma_f32_16x16x32_bf16 v[110:113], v[174:177], v[210:213], v[110:113]
	v_mfma_f32_16x16x32_bf16 v[106:109], v[182:185], v[210:213], v[106:109]
	s_waitcnt lgkmcnt(0)
	v_mfma_f32_16x16x32_bf16 v[102:105], v[174:177], v[218:221], v[102:105]
	v_mfma_f32_16x16x32_bf16 v[98:101], v[182:185], v[218:221], v[98:101]
	s_setprio 0
	s_barrier
	s_add_i32 s34, 0, 0x14000
	s_add_i32 s33, s33, s25
	v_add_u32_e32 v169, s34, v167
	v_lshl_add_u64 v[240:241], v[164:165], 0, v[138:139]
	s_mov_b32 m0, s33
	ds_read_b128 v[222:225], v169
	ds_read_b128 v[232:235], v169 offset:2048
	ds_read_b128 v[228:231], v169 offset:1024
	ds_read_b128 v[236:239], v169 offset:3072
	global_load_lds_dwordx4 v[240:241], off
	v_lshl_add_u64 v[242:243], v[164:165], 0, v[146:147]
	s_add_i32 m0, s33, 0x2000
	s_nop 0
	global_load_lds_dwordx4 v[242:243], off
	s_barrier
	s_setprio 1
	s_waitcnt lgkmcnt(3)
	v_mfma_f32_16x16x32_bf16 v[94:97], v[222:225], v[186:189], v[94:97]
	s_waitcnt lgkmcnt(2)
	v_mfma_f32_16x16x32_bf16 v[90:93], v[232:235], v[186:189], v[90:93]
	v_mfma_f32_16x16x32_bf16 v[86:89], v[222:225], v[194:197], v[86:89]
	v_mfma_f32_16x16x32_bf16 v[82:85], v[232:235], v[194:197], v[82:85]
	v_mfma_f32_16x16x32_bf16 v[78:81], v[222:225], v[202:205], v[78:81]
	v_mfma_f32_16x16x32_bf16 v[74:77], v[232:235], v[202:205], v[74:77]
	v_mfma_f32_16x16x32_bf16 v[70:73], v[222:225], v[214:217], v[70:73]
	v_mfma_f32_16x16x32_bf16 v[66:69], v[232:235], v[214:217], v[66:69]
	s_waitcnt lgkmcnt(1)
	v_mfma_f32_16x16x32_bf16 v[94:97], v[228:231], v[190:193], v[94:97]
	s_waitcnt lgkmcnt(0)
	v_mfma_f32_16x16x32_bf16 v[90:93], v[236:239], v[190:193], v[90:93]
	v_mfma_f32_16x16x32_bf16 v[86:89], v[228:231], v[198:201], v[86:89]
	v_mfma_f32_16x16x32_bf16 v[82:85], v[236:239], v[198:201], v[82:85]
	v_mfma_f32_16x16x32_bf16 v[78:81], v[228:231], v[210:213], v[78:81]
	v_mfma_f32_16x16x32_bf16 v[74:77], v[236:239], v[210:213], v[74:77]
	v_mfma_f32_16x16x32_bf16 v[70:73], v[228:231], v[218:221], v[70:73]
	v_mfma_f32_16x16x32_bf16 v[66:69], v[236:239], v[218:221], v[66:69]
	s_setprio 0
	s_mov_b32 m0, s17
	v_lshl_add_u64 v[244:245], v[206:207], 0, v[138:139]
	s_barrier
	ds_read_b128 v[186:189], v168 offset:16384
	ds_read_b128 v[194:197], v168 offset:18432
	ds_read_b128 v[202:205], v168 offset:20480
	ds_read_b128 v[214:217], v168 offset:22528
	ds_read_b128 v[190:193], v168 offset:17408
	ds_read_b128 v[198:201], v168 offset:19456
	ds_read_b128 v[210:213], v168 offset:21504
	ds_read_b128 v[218:221], v168 offset:23552
	global_load_lds_dwordx4 v[244:245], off
	v_lshl_add_u64 v[246:247], v[206:207], 0, v[146:147]
	s_mov_b32 m0, s26
	s_nop 0
	global_load_lds_dwordx4 v[246:247], off
	s_barrier
	s_setprio 1
	s_waitcnt lgkmcnt(7)
	v_mfma_f32_16x16x32_bf16 v[62:65], v[170:173], v[186:189], v[62:65]
	v_mfma_f32_16x16x32_bf16 v[58:61], v[178:181], v[186:189], v[58:61]
	s_waitcnt lgkmcnt(6)
	v_mfma_f32_16x16x32_bf16 v[54:57], v[170:173], v[194:197], v[54:57]
	v_mfma_f32_16x16x32_bf16 v[50:53], v[178:181], v[194:197], v[50:53]
	s_waitcnt lgkmcnt(5)
	v_mfma_f32_16x16x32_bf16 v[46:49], v[170:173], v[202:205], v[46:49]
	v_mfma_f32_16x16x32_bf16 v[42:45], v[178:181], v[202:205], v[42:45]
	s_waitcnt lgkmcnt(4)
	v_mfma_f32_16x16x32_bf16 v[38:41], v[170:173], v[214:217], v[38:41]
	v_mfma_f32_16x16x32_bf16 v[34:37], v[178:181], v[214:217], v[34:37]
	s_waitcnt lgkmcnt(3)
	v_mfma_f32_16x16x32_bf16 v[62:65], v[174:177], v[190:193], v[62:65]
	v_mfma_f32_16x16x32_bf16 v[58:61], v[182:185], v[190:193], v[58:61]
	s_waitcnt lgkmcnt(2)
	v_mfma_f32_16x16x32_bf16 v[54:57], v[174:177], v[198:201], v[54:57]
	v_mfma_f32_16x16x32_bf16 v[50:53], v[182:185], v[198:201], v[50:53]
	s_waitcnt lgkmcnt(1)
	v_mfma_f32_16x16x32_bf16 v[46:49], v[174:177], v[210:213], v[46:49]
	v_mfma_f32_16x16x32_bf16 v[42:45], v[182:185], v[210:213], v[42:45]
	s_waitcnt lgkmcnt(0)
	v_mfma_f32_16x16x32_bf16 v[38:41], v[174:177], v[218:221], v[38:41]
	v_mfma_f32_16x16x32_bf16 v[34:37], v[182:185], v[218:221], v[34:37]
	s_setprio 0
	s_barrier
	v_lshl_add_u64 v[170:171], v[164:165], 0, s[8:9]
	s_add_i32 s33, s34, s25
	v_lshl_add_u64 v[172:173], v[170:171], 0, v[138:139]
	s_mov_b32 m0, s33
	v_lshl_add_u64 v[170:171], v[170:171], 0, v[146:147]
	global_load_lds_dwordx4 v[172:173], off
	s_add_i32 m0, s33, 0x2000
	s_nop 0
	global_load_lds_dwordx4 v[170:171], off
	s_waitcnt vmcnt(6)
	s_barrier
	s_setprio 1
	v_mfma_f32_16x16x32_bf16 v[30:33], v[222:225], v[186:189], v[30:33]
	v_mfma_f32_16x16x32_bf16 v[26:29], v[232:235], v[186:189], v[26:29]
	v_mfma_f32_16x16x32_bf16 v[22:25], v[222:225], v[194:197], v[22:25]
	v_mfma_f32_16x16x32_bf16 v[18:21], v[232:235], v[194:197], v[18:21]
	v_mfma_f32_16x16x32_bf16 v[14:17], v[222:225], v[202:205], v[14:17]
	v_mfma_f32_16x16x32_bf16 v[10:13], v[232:235], v[202:205], v[10:13]
	v_mfma_f32_16x16x32_bf16 v[6:9], v[222:225], v[214:217], v[6:9]
	v_mfma_f32_16x16x32_bf16 v[2:5], v[232:235], v[214:217], v[2:5]
	v_mfma_f32_16x16x32_bf16 v[30:33], v[228:231], v[190:193], v[30:33]
	v_mfma_f32_16x16x32_bf16 v[26:29], v[236:239], v[190:193], v[26:29]
	v_mfma_f32_16x16x32_bf16 v[22:25], v[228:231], v[198:201], v[22:25]
	v_mfma_f32_16x16x32_bf16 v[18:21], v[236:239], v[198:201], v[18:21]
	v_mfma_f32_16x16x32_bf16 v[14:17], v[228:231], v[210:213], v[14:17]
	v_mfma_f32_16x16x32_bf16 v[10:13], v[236:239], v[210:213], v[10:13]
	v_mfma_f32_16x16x32_bf16 v[6:9], v[228:231], v[218:221], v[6:9]
	v_mfma_f32_16x16x32_bf16 v[2:5], v[236:239], v[218:221], v[2:5]
	s_setprio 0
	s_add_i32 s33, 0, 0x18000
	v_add_u32_e32 v169, s33, v167
	s_barrier
	ds_read_b128 v[170:173], v169
	ds_read_b128 v[178:181], v169 offset:2048
	ds_read_b128 v[174:177], v169 offset:1024
	ds_read_b128 v[182:185], v169 offset:3072
	v_lshl_add_u64 v[206:207], v[206:207], 0, s[8:9]
	s_mov_b32 m0, s27
	v_lshl_add_u64 v[222:223], v[206:207], 0, v[138:139]
	ds_read_b128 v[186:189], v168 offset:32768
	ds_read_b128 v[194:197], v168 offset:34816
	ds_read_b128 v[202:205], v168 offset:36864
	ds_read_b128 v[214:217], v168 offset:38912
	ds_read_b128 v[190:193], v168 offset:33792
	ds_read_b128 v[198:201], v168 offset:35840
	ds_read_b128 v[210:213], v168 offset:37888
	ds_read_b128 v[218:221], v168 offset:39936
	global_load_lds_dwordx4 v[222:223], off
	v_lshl_add_u64 v[206:207], v[206:207], 0, v[146:147]
	s_mov_b32 m0, s28
	s_nop 0
	global_load_lds_dwordx4 v[206:207], off
	s_waitcnt lgkmcnt(8)
	s_barrier
	s_setprio 1
	s_waitcnt lgkmcnt(7)
	v_mfma_f32_16x16x32_bf16 v[126:129], v[170:173], v[186:189], v[126:129]
	v_mfma_f32_16x16x32_bf16 v[122:125], v[178:181], v[186:189], v[122:125]
	s_waitcnt lgkmcnt(6)
	v_mfma_f32_16x16x32_bf16 v[118:121], v[170:173], v[194:197], v[118:121]
	v_mfma_f32_16x16x32_bf16 v[114:117], v[178:181], v[194:197], v[114:117]
	s_waitcnt lgkmcnt(5)
	v_mfma_f32_16x16x32_bf16 v[110:113], v[170:173], v[202:205], v[110:113]
	v_mfma_f32_16x16x32_bf16 v[106:109], v[178:181], v[202:205], v[106:109]
	s_waitcnt lgkmcnt(4)
	v_mfma_f32_16x16x32_bf16 v[102:105], v[170:173], v[214:217], v[102:105]
	v_mfma_f32_16x16x32_bf16 v[98:101], v[178:181], v[214:217], v[98:101]
	s_waitcnt lgkmcnt(3)
	v_mfma_f32_16x16x32_bf16 v[126:129], v[174:177], v[190:193], v[126:129]
	v_mfma_f32_16x16x32_bf16 v[122:125], v[182:185], v[190:193], v[122:125]
	s_waitcnt lgkmcnt(2)
	v_mfma_f32_16x16x32_bf16 v[118:121], v[174:177], v[198:201], v[118:121]
	v_mfma_f32_16x16x32_bf16 v[114:117], v[182:185], v[198:201], v[114:117]
	s_waitcnt lgkmcnt(1)
	v_mfma_f32_16x16x32_bf16 v[110:113], v[174:177], v[210:213], v[110:113]
	v_mfma_f32_16x16x32_bf16 v[106:109], v[182:185], v[210:213], v[106:109]
	s_waitcnt lgkmcnt(0)
	v_mfma_f32_16x16x32_bf16 v[102:105], v[174:177], v[218:221], v[102:105]
	v_mfma_f32_16x16x32_bf16 v[98:101], v[182:185], v[218:221], v[98:101]
	s_setprio 0
	s_barrier
	s_add_i32 s34, 0, 0x1c000
	s_add_i32 s33, s33, s25
	v_add_u32_e32 v169, s34, v167
	v_lshl_add_u64 v[206:207], v[240:241], 0, s[10:11]
	s_mov_b32 m0, s33
	ds_read_b128 v[222:225], v169
	ds_read_b128 v[232:235], v169 offset:2048
	ds_read_b128 v[228:231], v169 offset:1024
	ds_read_b128 v[236:239], v169 offset:3072
	global_load_lds_dwordx4 v[206:207], off
	v_lshl_add_u64 v[206:207], v[242:243], 0, s[10:11]
	s_add_i32 m0, s33, 0x2000
	s_nop 0
	global_load_lds_dwordx4 v[206:207], off
	s_barrier
	s_setprio 1
	s_waitcnt lgkmcnt(3)
	v_mfma_f32_16x16x32_bf16 v[94:97], v[222:225], v[186:189], v[94:97]
	s_waitcnt lgkmcnt(2)
	v_mfma_f32_16x16x32_bf16 v[90:93], v[232:235], v[186:189], v[90:93]
	v_mfma_f32_16x16x32_bf16 v[86:89], v[222:225], v[194:197], v[86:89]
	v_mfma_f32_16x16x32_bf16 v[82:85], v[232:235], v[194:197], v[82:85]
	v_mfma_f32_16x16x32_bf16 v[78:81], v[222:225], v[202:205], v[78:81]
	v_mfma_f32_16x16x32_bf16 v[74:77], v[232:235], v[202:205], v[74:77]
	v_mfma_f32_16x16x32_bf16 v[70:73], v[222:225], v[214:217], v[70:73]
	v_mfma_f32_16x16x32_bf16 v[66:69], v[232:235], v[214:217], v[66:69]
	s_waitcnt lgkmcnt(1)
	v_mfma_f32_16x16x32_bf16 v[94:97], v[228:231], v[190:193], v[94:97]
	s_waitcnt lgkmcnt(0)
	v_mfma_f32_16x16x32_bf16 v[90:93], v[236:239], v[190:193], v[90:93]
	v_mfma_f32_16x16x32_bf16 v[86:89], v[228:231], v[198:201], v[86:89]
	v_mfma_f32_16x16x32_bf16 v[82:85], v[236:239], v[198:201], v[82:85]
	v_mfma_f32_16x16x32_bf16 v[78:81], v[228:231], v[210:213], v[78:81]
	v_mfma_f32_16x16x32_bf16 v[74:77], v[236:239], v[210:213], v[74:77]
	v_mfma_f32_16x16x32_bf16 v[70:73], v[228:231], v[218:221], v[70:73]
	v_mfma_f32_16x16x32_bf16 v[66:69], v[236:239], v[218:221], v[66:69]
	s_setprio 0
	s_mov_b32 m0, s29
	v_lshl_add_u64 v[206:207], v[244:245], 0, s[10:11]
	s_barrier
	ds_read_b128 v[186:189], v168 offset:49152
	ds_read_b128 v[194:197], v168 offset:51200
	ds_read_b128 v[202:205], v168 offset:53248
	ds_read_b128 v[214:217], v168 offset:55296
	ds_read_b128 v[190:193], v168 offset:50176
	ds_read_b128 v[198:201], v168 offset:52224
	ds_read_b128 v[210:213], v168 offset:54272
	ds_read_b128 v[218:221], v168 offset:56320
	global_load_lds_dwordx4 v[206:207], off
	v_lshl_add_u64 v[206:207], v[246:247], 0, s[10:11]
	s_mov_b32 m0, s30
	s_nop 0
	global_load_lds_dwordx4 v[206:207], off
	s_barrier
	s_setprio 1
	s_waitcnt lgkmcnt(7)
	v_mfma_f32_16x16x32_bf16 v[62:65], v[170:173], v[186:189], v[62:65]
	v_mfma_f32_16x16x32_bf16 v[58:61], v[178:181], v[186:189], v[58:61]
	s_waitcnt lgkmcnt(6)
	v_mfma_f32_16x16x32_bf16 v[54:57], v[170:173], v[194:197], v[54:57]
	v_mfma_f32_16x16x32_bf16 v[50:53], v[178:181], v[194:197], v[50:53]
	s_waitcnt lgkmcnt(5)
	v_mfma_f32_16x16x32_bf16 v[46:49], v[170:173], v[202:205], v[46:49]
	v_mfma_f32_16x16x32_bf16 v[42:45], v[178:181], v[202:205], v[42:45]
	s_waitcnt lgkmcnt(4)
	v_mfma_f32_16x16x32_bf16 v[38:41], v[170:173], v[214:217], v[38:41]
	v_mfma_f32_16x16x32_bf16 v[34:37], v[178:181], v[214:217], v[34:37]
	s_waitcnt lgkmcnt(3)
	v_mfma_f32_16x16x32_bf16 v[62:65], v[174:177], v[190:193], v[62:65]
	v_mfma_f32_16x16x32_bf16 v[58:61], v[182:185], v[190:193], v[58:61]
	s_waitcnt lgkmcnt(2)
	v_mfma_f32_16x16x32_bf16 v[54:57], v[174:177], v[198:201], v[54:57]
	v_mfma_f32_16x16x32_bf16 v[50:53], v[182:185], v[198:201], v[50:53]
	s_waitcnt lgkmcnt(1)
	v_mfma_f32_16x16x32_bf16 v[46:49], v[174:177], v[210:213], v[46:49]
	v_mfma_f32_16x16x32_bf16 v[42:45], v[182:185], v[210:213], v[42:45]
	s_waitcnt lgkmcnt(0)
	v_mfma_f32_16x16x32_bf16 v[38:41], v[174:177], v[218:221], v[38:41]
	v_mfma_f32_16x16x32_bf16 v[34:37], v[182:185], v[218:221], v[34:37]
	s_setprio 0
	s_barrier
	v_lshl_add_u64 v[164:165], v[164:165], 0, s[12:13]
	s_add_i32 s33, s34, s25
	v_lshl_add_u64 v[170:171], v[164:165], 0, v[138:139]
	s_mov_b32 m0, s33
	v_lshl_add_u64 v[164:165], v[164:165], 0, v[146:147]
	global_load_lds_dwordx4 v[170:171], off
	s_add_i32 m0, s33, 0x2000
	s_nop 0
	global_load_lds_dwordx4 v[164:165], off
	s_waitcnt vmcnt(6)
	s_barrier
	s_setprio 1
	v_mfma_f32_16x16x32_bf16 v[30:33], v[222:225], v[186:189], v[30:33]
	v_mfma_f32_16x16x32_bf16 v[26:29], v[232:235], v[186:189], v[26:29]
	v_mfma_f32_16x16x32_bf16 v[22:25], v[222:225], v[194:197], v[22:25]
	v_mfma_f32_16x16x32_bf16 v[18:21], v[232:235], v[194:197], v[18:21]
	v_mfma_f32_16x16x32_bf16 v[14:17], v[222:225], v[202:205], v[14:17]
	v_mfma_f32_16x16x32_bf16 v[10:13], v[232:235], v[202:205], v[10:13]
	v_mfma_f32_16x16x32_bf16 v[6:9], v[222:225], v[214:217], v[6:9]
	v_mfma_f32_16x16x32_bf16 v[2:5], v[232:235], v[214:217], v[2:5]
	v_mfma_f32_16x16x32_bf16 v[30:33], v[228:231], v[190:193], v[30:33]
	v_mfma_f32_16x16x32_bf16 v[26:29], v[236:239], v[190:193], v[26:29]
	v_mfma_f32_16x16x32_bf16 v[22:25], v[228:231], v[198:201], v[22:25]
	v_mfma_f32_16x16x32_bf16 v[18:21], v[236:239], v[198:201], v[18:21]
	v_mfma_f32_16x16x32_bf16 v[14:17], v[228:231], v[210:213], v[14:17]
	v_mfma_f32_16x16x32_bf16 v[10:13], v[236:239], v[210:213], v[10:13]
	v_mfma_f32_16x16x32_bf16 v[6:9], v[228:231], v[218:221], v[6:9]
	v_mfma_f32_16x16x32_bf16 v[2:5], v[236:239], v[218:221], v[2:5]
	s_setprio 0
	s_add_i32 s31, s31, 2
	s_add_u32 s6, s6, 0x100
	s_addc_u32 s7, s7, 0
	s_cmp_lt_u32 s31, 14
	s_barrier
	s_cbranch_scc1 .LBB0_1645
	s_waitcnt vmcnt(0)
	s_cmpk_gt_u32 s24, 0xff
	s_cbranch_scc1 .LBB0_1648
	s_barrier

.LBB0_1788:
	s_cmpk_eq_i32 s4, 0x700
	v_lshl_add_u64 v[170:171], v[162:163], 0, s[4:5]
	v_lshl_add_u64 v[170:171], v[170:171], 0, s[22:23]
	s_cselect_b64 vcc, -1, 0
	s_add_i32 s7, 0, 0x10000
	v_cndmask_b32_e32 v245, v171, v153, vcc
	v_add_u32_e32 v171, s7, v173
	ds_read_b128 v[176:179], v171
	ds_read_b128 v[184:187], v171 offset:2048
	ds_read_b128 v[180:183], v171 offset:1024
	ds_read_b128 v[188:191], v171 offset:3072
	v_cndmask_b32_e32 v244, v170, v152, vcc
	v_lshl_add_u64 v[170:171], v[168:169], 0, s[4:5]
	v_cndmask_b32_e32 v171, v171, v151, vcc
	v_cndmask_b32_e32 v170, v170, v150, vcc
	v_lshl_add_u64 v[228:229], v[164:165], 0, s[4:5]
	s_add_i32 m0, s34, 0xc000
	ds_read_b128 v[192:195], v174
	ds_read_b128 v[200:203], v174 offset:2048
	ds_read_b128 v[210:213], v174 offset:4096
	ds_read_b128 v[218:221], v174 offset:6144
	ds_read_b128 v[196:199], v174 offset:1024
	ds_read_b128 v[204:207], v174 offset:3072
	ds_read_b128 v[214:217], v174 offset:5120
	ds_read_b128 v[222:225], v174 offset:7168
	global_load_lds_dwordx4 v[228:229], off
	v_lshl_add_u64 v[228:229], v[166:167], 0, s[4:5]
	s_add_i32 m0, s34, 0xe000
	s_nop 0
	global_load_lds_dwordx4 v[228:229], off
	s_waitcnt lgkmcnt(8)
	s_barrier
	s_setprio 1
	s_waitcnt lgkmcnt(7)
	v_mfma_f32_16x16x32_bf16 v[126:129], v[176:179], v[192:195], v[126:129]
	v_mfma_f32_16x16x32_bf16 v[122:125], v[184:187], v[192:195], v[122:125]
	s_waitcnt lgkmcnt(6)
	v_mfma_f32_16x16x32_bf16 v[118:121], v[176:179], v[200:203], v[118:121]
	v_mfma_f32_16x16x32_bf16 v[114:117], v[184:187], v[200:203], v[114:117]
	s_waitcnt lgkmcnt(5)
	v_mfma_f32_16x16x32_bf16 v[110:113], v[176:179], v[210:213], v[110:113]
	v_mfma_f32_16x16x32_bf16 v[106:109], v[184:187], v[210:213], v[106:109]
	s_waitcnt lgkmcnt(4)
	v_mfma_f32_16x16x32_bf16 v[102:105], v[176:179], v[218:221], v[102:105]
	v_mfma_f32_16x16x32_bf16 v[98:101], v[184:187], v[218:221], v[98:101]
	s_waitcnt lgkmcnt(3)
	v_mfma_f32_16x16x32_bf16 v[126:129], v[180:183], v[196:199], v[126:129]
	v_mfma_f32_16x16x32_bf16 v[122:125], v[188:191], v[196:199], v[122:125]
	s_waitcnt lgkmcnt(2)
	v_mfma_f32_16x16x32_bf16 v[118:121], v[180:183], v[204:207], v[118:121]
	v_mfma_f32_16x16x32_bf16 v[114:117], v[188:191], v[204:207], v[114:117]
	s_waitcnt lgkmcnt(1)
	v_mfma_f32_16x16x32_bf16 v[110:113], v[180:183], v[214:217], v[110:113]
	v_mfma_f32_16x16x32_bf16 v[106:109], v[188:191], v[214:217], v[106:109]
	s_waitcnt lgkmcnt(0)
	v_mfma_f32_16x16x32_bf16 v[102:105], v[180:183], v[222:225], v[102:105]
	v_mfma_f32_16x16x32_bf16 v[98:101], v[188:191], v[222:225], v[98:101]
	s_setprio 0
	s_barrier
	s_add_i32 s57, 0, 0x14000
	s_add_i32 s7, s7, s39
	v_add_u32_e32 v175, s57, v173
	v_lshl_add_u64 v[246:247], v[170:171], 0, v[138:139]
	s_mov_b32 m0, s7
	ds_read_b128 v[228:231], v175
	ds_read_b128 v[236:239], v175 offset:2048
	ds_read_b128 v[232:235], v175 offset:1024
	ds_read_b128 v[240:243], v175 offset:3072
	global_load_lds_dwordx4 v[246:247], off
	v_lshl_add_u64 v[248:249], v[170:171], 0, v[148:149]
	s_add_i32 m0, s7, 0x2000
	s_nop 0
	global_load_lds_dwordx4 v[248:249], off
	s_barrier
	s_setprio 1
	s_waitcnt lgkmcnt(3)
	v_mfma_f32_16x16x32_bf16 v[94:97], v[228:231], v[192:195], v[94:97]
	s_waitcnt lgkmcnt(2)
	v_mfma_f32_16x16x32_bf16 v[90:93], v[236:239], v[192:195], v[90:93]
	v_mfma_f32_16x16x32_bf16 v[86:89], v[228:231], v[200:203], v[86:89]
	v_mfma_f32_16x16x32_bf16 v[82:85], v[236:239], v[200:203], v[82:85]
	v_mfma_f32_16x16x32_bf16 v[78:81], v[228:231], v[210:213], v[78:81]
	v_mfma_f32_16x16x32_bf16 v[74:77], v[236:239], v[210:213], v[74:77]
	v_mfma_f32_16x16x32_bf16 v[70:73], v[228:231], v[218:221], v[70:73]
	v_mfma_f32_16x16x32_bf16 v[66:69], v[236:239], v[218:221], v[66:69]
	s_waitcnt lgkmcnt(1)
	v_mfma_f32_16x16x32_bf16 v[94:97], v[232:235], v[196:199], v[94:97]
	s_waitcnt lgkmcnt(0)
	v_mfma_f32_16x16x32_bf16 v[90:93], v[240:243], v[196:199], v[90:93]
	v_mfma_f32_16x16x32_bf16 v[86:89], v[232:235], v[204:207], v[86:89]
	v_mfma_f32_16x16x32_bf16 v[82:85], v[240:243], v[204:207], v[82:85]
	v_mfma_f32_16x16x32_bf16 v[78:81], v[232:235], v[214:217], v[78:81]
	v_mfma_f32_16x16x32_bf16 v[74:77], v[240:243], v[214:217], v[74:77]
	v_mfma_f32_16x16x32_bf16 v[70:73], v[232:235], v[222:225], v[70:73]
	v_mfma_f32_16x16x32_bf16 v[66:69], v[240:243], v[222:225], v[66:69]
	s_setprio 0
	s_mov_b32 m0, s34
	v_lshl_add_u64 v[250:251], v[244:245], 0, v[138:139]
	s_barrier
	ds_read_b128 v[192:195], v174 offset:16384
	ds_read_b128 v[200:203], v174 offset:18432
	ds_read_b128 v[210:213], v174 offset:20480
	ds_read_b128 v[218:221], v174 offset:22528
	ds_read_b128 v[196:199], v174 offset:17408
	ds_read_b128 v[204:207], v174 offset:19456
	ds_read_b128 v[214:217], v174 offset:21504
	ds_read_b128 v[222:225], v174 offset:23552
	global_load_lds_dwordx4 v[250:251], off
	v_lshl_add_u64 v[252:253], v[244:245], 0, v[148:149]
	s_mov_b32 m0, s41
	s_nop 0
	global_load_lds_dwordx4 v[252:253], off
	s_barrier
	s_setprio 1
	s_waitcnt lgkmcnt(7)
	v_mfma_f32_16x16x32_bf16 v[62:65], v[176:179], v[192:195], v[62:65]
	v_mfma_f32_16x16x32_bf16 v[58:61], v[184:187], v[192:195], v[58:61]
	s_waitcnt lgkmcnt(6)
	v_mfma_f32_16x16x32_bf16 v[54:57], v[176:179], v[200:203], v[54:57]
	v_mfma_f32_16x16x32_bf16 v[50:53], v[184:187], v[200:203], v[50:53]
	s_waitcnt lgkmcnt(5)
	v_mfma_f32_16x16x32_bf16 v[46:49], v[176:179], v[210:213], v[46:49]
	v_mfma_f32_16x16x32_bf16 v[42:45], v[184:187], v[210:213], v[42:45]
	s_waitcnt lgkmcnt(4)
	v_mfma_f32_16x16x32_bf16 v[38:41], v[176:179], v[218:221], v[38:41]
	v_mfma_f32_16x16x32_bf16 v[34:37], v[184:187], v[218:221], v[34:37]
	s_waitcnt lgkmcnt(3)
	v_mfma_f32_16x16x32_bf16 v[62:65], v[180:183], v[196:199], v[62:65]
	v_mfma_f32_16x16x32_bf16 v[58:61], v[188:191], v[196:199], v[58:61]
	s_waitcnt lgkmcnt(2)
	v_mfma_f32_16x16x32_bf16 v[54:57], v[180:183], v[204:207], v[54:57]
	v_mfma_f32_16x16x32_bf16 v[50:53], v[188:191], v[204:207], v[50:53]
	s_waitcnt lgkmcnt(1)
	v_mfma_f32_16x16x32_bf16 v[46:49], v[180:183], v[214:217], v[46:49]
	v_mfma_f32_16x16x32_bf16 v[42:45], v[188:191], v[214:217], v[42:45]
	s_waitcnt lgkmcnt(0)
	v_mfma_f32_16x16x32_bf16 v[38:41], v[180:183], v[222:225], v[38:41]
	v_mfma_f32_16x16x32_bf16 v[34:37], v[188:191], v[222:225], v[34:37]
	s_setprio 0
	s_barrier
	v_lshl_add_u64 v[176:177], v[170:171], 0, s[16:17]
	s_add_i32 s7, s57, s39
	v_lshl_add_u64 v[178:179], v[176:177], 0, v[138:139]
	s_mov_b32 m0, s7
	v_lshl_add_u64 v[176:177], v[176:177], 0, v[148:149]
	global_load_lds_dwordx4 v[178:179], off
	s_add_i32 m0, s7, 0x2000
	s_nop 0
	global_load_lds_dwordx4 v[176:177], off
	s_waitcnt vmcnt(6)
	s_barrier
	s_setprio 1
	v_mfma_f32_16x16x32_bf16 v[30:33], v[228:231], v[192:195], v[30:33]
	v_mfma_f32_16x16x32_bf16 v[26:29], v[236:239], v[192:195], v[26:29]
	v_mfma_f32_16x16x32_bf16 v[22:25], v[228:231], v[200:203], v[22:25]
	v_mfma_f32_16x16x32_bf16 v[18:21], v[236:239], v[200:203], v[18:21]
	v_mfma_f32_16x16x32_bf16 v[14:17], v[228:231], v[210:213], v[14:17]
	v_mfma_f32_16x16x32_bf16 v[10:13], v[236:239], v[210:213], v[10:13]
	v_mfma_f32_16x16x32_bf16 v[6:9], v[228:231], v[218:221], v[6:9]
	v_mfma_f32_16x16x32_bf16 v[2:5], v[236:239], v[218:221], v[2:5]
	v_mfma_f32_16x16x32_bf16 v[30:33], v[232:235], v[196:199], v[30:33]
	v_mfma_f32_16x16x32_bf16 v[26:29], v[240:243], v[196:199], v[26:29]
	v_mfma_f32_16x16x32_bf16 v[22:25], v[232:235], v[204:207], v[22:25]
	v_mfma_f32_16x16x32_bf16 v[18:21], v[240:243], v[204:207], v[18:21]
	v_mfma_f32_16x16x32_bf16 v[14:17], v[232:235], v[214:217], v[14:17]
	v_mfma_f32_16x16x32_bf16 v[10:13], v[240:243], v[214:217], v[10:13]
	v_mfma_f32_16x16x32_bf16 v[6:9], v[232:235], v[222:225], v[6:9]
	v_mfma_f32_16x16x32_bf16 v[2:5], v[240:243], v[222:225], v[2:5]
	s_setprio 0
	s_add_i32 s7, 0, 0x18000
	v_add_u32_e32 v175, s7, v173
	s_barrier
	ds_read_b128 v[176:179], v175
	ds_read_b128 v[184:187], v175 offset:2048
	ds_read_b128 v[180:183], v175 offset:1024
	ds_read_b128 v[188:191], v175 offset:3072
	v_lshl_add_u64 v[228:229], v[244:245], 0, s[16:17]
	s_mov_b32 m0, s42
	v_lshl_add_u64 v[230:231], v[228:229], 0, v[138:139]
	ds_read_b128 v[192:195], v174 offset:32768
	ds_read_b128 v[200:203], v174 offset:34816
	ds_read_b128 v[210:213], v174 offset:36864
	ds_read_b128 v[218:221], v174 offset:38912
	ds_read_b128 v[196:199], v174 offset:33792
	ds_read_b128 v[204:207], v174 offset:35840
	ds_read_b128 v[214:217], v174 offset:37888
	ds_read_b128 v[222:225], v174 offset:39936
	global_load_lds_dwordx4 v[230:231], off
	v_lshl_add_u64 v[228:229], v[228:229], 0, v[148:149]
	s_mov_b32 m0, s43
	s_nop 0
	global_load_lds_dwordx4 v[228:229], off
	s_waitcnt lgkmcnt(8)
	s_barrier
	s_setprio 1
	s_waitcnt lgkmcnt(7)
	v_mfma_f32_16x16x32_bf16 v[126:129], v[176:179], v[192:195], v[126:129]
	v_mfma_f32_16x16x32_bf16 v[122:125], v[184:187], v[192:195], v[122:125]
	s_waitcnt lgkmcnt(6)
	v_mfma_f32_16x16x32_bf16 v[118:121], v[176:179], v[200:203], v[118:121]
	v_mfma_f32_16x16x32_bf16 v[114:117], v[184:187], v[200:203], v[114:117]
	s_waitcnt lgkmcnt(5)
	v_mfma_f32_16x16x32_bf16 v[110:113], v[176:179], v[210:213], v[110:113]
	v_mfma_f32_16x16x32_bf16 v[106:109], v[184:187], v[210:213], v[106:109]
	s_waitcnt lgkmcnt(4)
	v_mfma_f32_16x16x32_bf16 v[102:105], v[176:179], v[218:221], v[102:105]
	v_mfma_f32_16x16x32_bf16 v[98:101], v[184:187], v[218:221], v[98:101]
	s_waitcnt lgkmcnt(3)
	v_mfma_f32_16x16x32_bf16 v[126:129], v[180:183], v[196:199], v[126:129]
	v_mfma_f32_16x16x32_bf16 v[122:125], v[188:191], v[196:199], v[122:125]
	s_waitcnt lgkmcnt(2)
	v_mfma_f32_16x16x32_bf16 v[118:121], v[180:183], v[204:207], v[118:121]
	v_mfma_f32_16x16x32_bf16 v[114:117], v[188:191], v[204:207], v[114:117]
	s_waitcnt lgkmcnt(1)
	v_mfma_f32_16x16x32_bf16 v[110:113], v[180:183], v[214:217], v[110:113]
	v_mfma_f32_16x16x32_bf16 v[106:109], v[188:191], v[214:217], v[106:109]
	s_waitcnt lgkmcnt(0)
	v_mfma_f32_16x16x32_bf16 v[102:105], v[180:183], v[222:225], v[102:105]
	v_mfma_f32_16x16x32_bf16 v[98:101], v[188:191], v[222:225], v[98:101]
	s_setprio 0
	s_barrier
	s_add_i32 s57, 0, 0x1c000
	s_add_i32 s7, s7, s39
	v_add_u32_e32 v175, s57, v173
	v_lshl_add_u64 v[244:245], v[246:247], 0, s[18:19]
	s_mov_b32 m0, s7
	ds_read_b128 v[228:231], v175
	ds_read_b128 v[236:239], v175 offset:2048
	ds_read_b128 v[232:235], v175 offset:1024
	ds_read_b128 v[240:243], v175 offset:3072
	global_load_lds_dwordx4 v[244:245], off
	v_lshl_add_u64 v[244:245], v[248:249], 0, s[18:19]
	s_add_i32 m0, s7, 0x2000
	s_nop 0
	global_load_lds_dwordx4 v[244:245], off
	s_barrier
	s_setprio 1
	s_waitcnt lgkmcnt(3)
	v_mfma_f32_16x16x32_bf16 v[94:97], v[228:231], v[192:195], v[94:97]
	s_waitcnt lgkmcnt(2)
	v_mfma_f32_16x16x32_bf16 v[90:93], v[236:239], v[192:195], v[90:93]
	v_mfma_f32_16x16x32_bf16 v[86:89], v[228:231], v[200:203], v[86:89]
	v_mfma_f32_16x16x32_bf16 v[82:85], v[236:239], v[200:203], v[82:85]
	v_mfma_f32_16x16x32_bf16 v[78:81], v[228:231], v[210:213], v[78:81]
	v_mfma_f32_16x16x32_bf16 v[74:77], v[236:239], v[210:213], v[74:77]
	v_mfma_f32_16x16x32_bf16 v[70:73], v[228:231], v[218:221], v[70:73]
	v_mfma_f32_16x16x32_bf16 v[66:69], v[236:239], v[218:221], v[66:69]
	s_waitcnt lgkmcnt(1)
	v_mfma_f32_16x16x32_bf16 v[94:97], v[232:235], v[196:199], v[94:97]
	s_waitcnt lgkmcnt(0)
	v_mfma_f32_16x16x32_bf16 v[90:93], v[240:243], v[196:199], v[90:93]
	v_mfma_f32_16x16x32_bf16 v[86:89], v[232:235], v[204:207], v[86:89]
	v_mfma_f32_16x16x32_bf16 v[82:85], v[240:243], v[204:207], v[82:85]
	v_mfma_f32_16x16x32_bf16 v[78:81], v[232:235], v[214:217], v[78:81]
	v_mfma_f32_16x16x32_bf16 v[74:77], v[240:243], v[214:217], v[74:77]
	v_mfma_f32_16x16x32_bf16 v[70:73], v[232:235], v[222:225], v[70:73]
	v_mfma_f32_16x16x32_bf16 v[66:69], v[240:243], v[222:225], v[66:69]
	s_setprio 0
	s_mov_b32 m0, s55
	v_lshl_add_u64 v[244:245], v[250:251], 0, s[18:19]
	s_barrier
	ds_read_b128 v[192:195], v174 offset:49152
	ds_read_b128 v[200:203], v174 offset:51200
	ds_read_b128 v[210:213], v174 offset:53248
	ds_read_b128 v[218:221], v174 offset:55296
	ds_read_b128 v[196:199], v174 offset:50176
	ds_read_b128 v[204:207], v174 offset:52224
	ds_read_b128 v[214:217], v174 offset:54272
	ds_read_b128 v[222:225], v174 offset:56320
	global_load_lds_dwordx4 v[244:245], off
	v_lshl_add_u64 v[244:245], v[252:253], 0, s[18:19]
	s_mov_b32 m0, s56
	s_nop 0
	global_load_lds_dwordx4 v[244:245], off
	s_barrier
	s_setprio 1
	s_waitcnt lgkmcnt(7)
	v_mfma_f32_16x16x32_bf16 v[62:65], v[176:179], v[192:195], v[62:65]
	v_mfma_f32_16x16x32_bf16 v[58:61], v[184:187], v[192:195], v[58:61]
	s_waitcnt lgkmcnt(6)
	v_mfma_f32_16x16x32_bf16 v[54:57], v[176:179], v[200:203], v[54:57]
	v_mfma_f32_16x16x32_bf16 v[50:53], v[184:187], v[200:203], v[50:53]
	s_waitcnt lgkmcnt(5)
	v_mfma_f32_16x16x32_bf16 v[46:49], v[176:179], v[210:213], v[46:49]
	v_mfma_f32_16x16x32_bf16 v[42:45], v[184:187], v[210:213], v[42:45]
	s_waitcnt lgkmcnt(4)
	v_mfma_f32_16x16x32_bf16 v[38:41], v[176:179], v[218:221], v[38:41]
	v_mfma_f32_16x16x32_bf16 v[34:37], v[184:187], v[218:221], v[34:37]
	s_waitcnt lgkmcnt(3)
	v_mfma_f32_16x16x32_bf16 v[62:65], v[180:183], v[196:199], v[62:65]
	v_mfma_f32_16x16x32_bf16 v[58:61], v[188:191], v[196:199], v[58:61]
	s_waitcnt lgkmcnt(2)
	v_mfma_f32_16x16x32_bf16 v[54:57], v[180:183], v[204:207], v[54:57]
	v_mfma_f32_16x16x32_bf16 v[50:53], v[188:191], v[204:207], v[50:53]
	s_waitcnt lgkmcnt(1)
	v_mfma_f32_16x16x32_bf16 v[46:49], v[180:183], v[214:217], v[46:49]
	v_mfma_f32_16x16x32_bf16 v[42:45], v[188:191], v[214:217], v[42:45]
	s_waitcnt lgkmcnt(0)
	v_mfma_f32_16x16x32_bf16 v[38:41], v[180:183], v[222:225], v[38:41]
	v_mfma_f32_16x16x32_bf16 v[34:37], v[188:191], v[222:225], v[34:37]
	s_setprio 0
	s_barrier
	v_lshl_add_u64 v[170:171], v[170:171], 0, s[20:21]
	s_add_i32 s7, s57, s39
	v_lshl_add_u64 v[176:177], v[170:171], 0, v[138:139]
	s_mov_b32 m0, s7
	v_lshl_add_u64 v[170:171], v[170:171], 0, v[148:149]
	global_load_lds_dwordx4 v[176:177], off
	s_add_i32 m0, s7, 0x2000
	s_nop 0
	global_load_lds_dwordx4 v[170:171], off
	s_waitcnt vmcnt(6)
	s_barrier
	s_setprio 1
	v_mfma_f32_16x16x32_bf16 v[30:33], v[228:231], v[192:195], v[30:33]
	v_mfma_f32_16x16x32_bf16 v[26:29], v[236:239], v[192:195], v[26:29]
	v_mfma_f32_16x16x32_bf16 v[22:25], v[228:231], v[200:203], v[22:25]
	v_mfma_f32_16x16x32_bf16 v[18:21], v[236:239], v[200:203], v[18:21]
	v_mfma_f32_16x16x32_bf16 v[14:17], v[228:231], v[210:213], v[14:17]
	v_mfma_f32_16x16x32_bf16 v[10:13], v[236:239], v[210:213], v[10:13]
	v_mfma_f32_16x16x32_bf16 v[6:9], v[228:231], v[218:221], v[6:9]
	v_mfma_f32_16x16x32_bf16 v[2:5], v[236:239], v[218:221], v[2:5]
	v_mfma_f32_16x16x32_bf16 v[30:33], v[232:235], v[196:199], v[30:33]
	v_mfma_f32_16x16x32_bf16 v[26:29], v[240:243], v[196:199], v[26:29]
	v_mfma_f32_16x16x32_bf16 v[22:25], v[232:235], v[204:207], v[22:25]
	v_mfma_f32_16x16x32_bf16 v[18:21], v[240:243], v[204:207], v[18:21]
	v_mfma_f32_16x16x32_bf16 v[14:17], v[232:235], v[214:217], v[14:17]
	v_mfma_f32_16x16x32_bf16 v[10:13], v[240:243], v[214:217], v[10:13]
	v_mfma_f32_16x16x32_bf16 v[6:9], v[232:235], v[222:225], v[6:9]
	v_mfma_f32_16x16x32_bf16 v[2:5], v[240:243], v[222:225], v[2:5]
	s_setprio 0
	s_add_i32 s6, s6, 2
	s_add_u32 s4, s4, 0x100
	s_addc_u32 s5, s5, 0
	s_cmp_lt_u32 s6, 14
	s_barrier
	s_cbranch_scc1 .LBB0_1788
	s_waitcnt vmcnt(0)
	s_cmpk_gt_u32 s38, 0xff
	s_cbranch_scc1 .LBB0_1791
	s_barrier

.LBB0_1914:
	s_add_u32 s38, s4, 0xf8cd0080
	s_addc_u32 s39, s5, -1
	s_cmp_lg_u32 s37, 40
	s_cselect_b32 s39, s39, 0
	s_cselect_b32 s38, s38, 0
	s_add_i32 s40, 0, 0x10000
	v_add_u32_e32 v156, s40, v162
	ds_read_b128 v[164:167], v156
	ds_read_b128 v[172:175], v156 offset:2048
	ds_read_b128 v[168:171], v156 offset:1024
	ds_read_b128 v[176:179], v156 offset:3072
	v_lshl_add_u64 v[232:233], v[148:149], 0, s[38:39]
	v_lshl_add_u64 v[156:157], v[146:147], 0, s[38:39]
	v_lshl_add_u64 v[214:215], v[150:151], 0, s[4:5]
	s_add_i32 m0, s28, 0xc000
	ds_read_b128 v[180:183], v163
	ds_read_b128 v[188:191], v163 offset:2048
	ds_read_b128 v[196:199], v163 offset:4096
	ds_read_b128 v[204:207], v163 offset:6144
	ds_read_b128 v[184:187], v163 offset:1024
	ds_read_b128 v[192:195], v163 offset:3072
	ds_read_b128 v[200:203], v163 offset:5120
	ds_read_b128 v[210:213], v163 offset:7168
	global_load_lds_dwordx4 v[214:215], off
	v_lshl_add_u64 v[214:215], v[152:153], 0, s[4:5]
	s_add_i32 m0, s28, 0xe000
	s_nop 0
	global_load_lds_dwordx4 v[214:215], off
	s_waitcnt lgkmcnt(8)
	s_barrier
	s_setprio 1
	s_waitcnt lgkmcnt(7)
	v_mfma_f32_16x16x32_bf16 v[126:129], v[164:167], v[180:183], v[126:129]
	v_mfma_f32_16x16x32_bf16 v[122:125], v[172:175], v[180:183], v[122:125]
	s_waitcnt lgkmcnt(6)
	v_mfma_f32_16x16x32_bf16 v[118:121], v[164:167], v[188:191], v[118:121]
	v_mfma_f32_16x16x32_bf16 v[114:117], v[172:175], v[188:191], v[114:117]
	s_waitcnt lgkmcnt(5)
	v_mfma_f32_16x16x32_bf16 v[110:113], v[164:167], v[196:199], v[110:113]
	v_mfma_f32_16x16x32_bf16 v[106:109], v[172:175], v[196:199], v[106:109]
	s_waitcnt lgkmcnt(4)
	v_mfma_f32_16x16x32_bf16 v[102:105], v[164:167], v[204:207], v[102:105]
	v_mfma_f32_16x16x32_bf16 v[98:101], v[172:175], v[204:207], v[98:101]
	s_waitcnt lgkmcnt(3)
	v_mfma_f32_16x16x32_bf16 v[126:129], v[168:171], v[184:187], v[126:129]
	v_mfma_f32_16x16x32_bf16 v[122:125], v[176:179], v[184:187], v[122:125]
	s_waitcnt lgkmcnt(2)
	v_mfma_f32_16x16x32_bf16 v[118:121], v[168:171], v[192:195], v[118:121]
	v_mfma_f32_16x16x32_bf16 v[114:117], v[176:179], v[192:195], v[114:117]
	s_waitcnt lgkmcnt(1)
	v_mfma_f32_16x16x32_bf16 v[110:113], v[168:171], v[200:203], v[110:113]
	v_mfma_f32_16x16x32_bf16 v[106:109], v[176:179], v[200:203], v[106:109]
	s_waitcnt lgkmcnt(0)
	v_mfma_f32_16x16x32_bf16 v[102:105], v[168:171], v[210:213], v[102:105]
	v_mfma_f32_16x16x32_bf16 v[98:101], v[176:179], v[210:213], v[98:101]
	s_setprio 0
	s_barrier
	s_add_i32 s38, 0, 0x14000
	s_add_i32 s39, s40, s27
	v_add_u32_e32 v208, s38, v162
	v_lshl_add_u64 v[234:235], v[156:157], 0, v[130:131]
	s_mov_b32 m0, s39
	ds_read_b128 v[214:217], v208
	ds_read_b128 v[222:225], v208 offset:2048
	ds_read_b128 v[218:221], v208 offset:1024
	ds_read_b128 v[228:231], v208 offset:3072
	global_load_lds_dwordx4 v[234:235], off
	v_lshl_add_u64 v[236:237], v[156:157], 0, v[144:145]
	s_add_i32 m0, s39, 0x2000
	s_nop 0
	global_load_lds_dwordx4 v[236:237], off
	s_barrier
	s_setprio 1
	s_waitcnt lgkmcnt(3)
	v_mfma_f32_16x16x32_bf16 v[94:97], v[214:217], v[180:183], v[94:97]
	s_waitcnt lgkmcnt(2)
	v_mfma_f32_16x16x32_bf16 v[90:93], v[222:225], v[180:183], v[90:93]
	v_mfma_f32_16x16x32_bf16 v[86:89], v[214:217], v[188:191], v[86:89]
	v_mfma_f32_16x16x32_bf16 v[82:85], v[222:225], v[188:191], v[82:85]
	v_mfma_f32_16x16x32_bf16 v[78:81], v[214:217], v[196:199], v[78:81]
	v_mfma_f32_16x16x32_bf16 v[74:77], v[222:225], v[196:199], v[74:77]
	v_mfma_f32_16x16x32_bf16 v[70:73], v[214:217], v[204:207], v[70:73]
	v_mfma_f32_16x16x32_bf16 v[66:69], v[222:225], v[204:207], v[66:69]
	s_waitcnt lgkmcnt(1)
	v_mfma_f32_16x16x32_bf16 v[94:97], v[218:221], v[184:187], v[94:97]
	s_waitcnt lgkmcnt(0)
	v_mfma_f32_16x16x32_bf16 v[90:93], v[228:231], v[184:187], v[90:93]
	v_mfma_f32_16x16x32_bf16 v[86:89], v[218:221], v[192:195], v[86:89]
	v_mfma_f32_16x16x32_bf16 v[82:85], v[228:231], v[192:195], v[82:85]
	v_mfma_f32_16x16x32_bf16 v[78:81], v[218:221], v[200:203], v[78:81]
	v_mfma_f32_16x16x32_bf16 v[74:77], v[228:231], v[200:203], v[74:77]
	v_mfma_f32_16x16x32_bf16 v[70:73], v[218:221], v[210:213], v[70:73]
	v_mfma_f32_16x16x32_bf16 v[66:69], v[228:231], v[210:213], v[66:69]
	s_setprio 0
	s_mov_b32 m0, s28
	v_lshl_add_u64 v[238:239], v[232:233], 0, v[130:131]
	s_barrier
	ds_read_b128 v[180:183], v163 offset:16384
	ds_read_b128 v[188:191], v163 offset:18432
	ds_read_b128 v[196:199], v163 offset:20480
	ds_read_b128 v[204:207], v163 offset:22528
	ds_read_b128 v[184:187], v163 offset:17408
	ds_read_b128 v[192:195], v163 offset:19456
	ds_read_b128 v[200:203], v163 offset:21504
	ds_read_b128 v[210:213], v163 offset:23552
	global_load_lds_dwordx4 v[238:239], off
	v_lshl_add_u64 v[240:241], v[232:233], 0, v[144:145]
	s_mov_b32 m0, s29
	s_nop 0
	global_load_lds_dwordx4 v[240:241], off
	s_barrier
	s_setprio 1
	s_waitcnt lgkmcnt(7)
	v_mfma_f32_16x16x32_bf16 v[62:65], v[164:167], v[180:183], v[62:65]
	v_mfma_f32_16x16x32_bf16 v[58:61], v[172:175], v[180:183], v[58:61]
	s_waitcnt lgkmcnt(6)
	v_mfma_f32_16x16x32_bf16 v[54:57], v[164:167], v[188:191], v[54:57]
	v_mfma_f32_16x16x32_bf16 v[50:53], v[172:175], v[188:191], v[50:53]
	s_waitcnt lgkmcnt(5)
	v_mfma_f32_16x16x32_bf16 v[46:49], v[164:167], v[196:199], v[46:49]
	v_mfma_f32_16x16x32_bf16 v[42:45], v[172:175], v[196:199], v[42:45]
	s_waitcnt lgkmcnt(4)
	v_mfma_f32_16x16x32_bf16 v[38:41], v[164:167], v[204:207], v[38:41]
	v_mfma_f32_16x16x32_bf16 v[34:37], v[172:175], v[204:207], v[34:37]
	s_waitcnt lgkmcnt(3)
	v_mfma_f32_16x16x32_bf16 v[62:65], v[168:171], v[184:187], v[62:65]
	v_mfma_f32_16x16x32_bf16 v[58:61], v[176:179], v[184:187], v[58:61]
	s_waitcnt lgkmcnt(2)
	v_mfma_f32_16x16x32_bf16 v[54:57], v[168:171], v[192:195], v[54:57]
	v_mfma_f32_16x16x32_bf16 v[50:53], v[176:179], v[192:195], v[50:53]
	s_waitcnt lgkmcnt(1)
	v_mfma_f32_16x16x32_bf16 v[46:49], v[168:171], v[200:203], v[46:49]
	v_mfma_f32_16x16x32_bf16 v[42:45], v[176:179], v[200:203], v[42:45]
	s_waitcnt lgkmcnt(0)
	v_mfma_f32_16x16x32_bf16 v[38:41], v[168:171], v[210:213], v[38:41]
	v_mfma_f32_16x16x32_bf16 v[34:37], v[176:179], v[210:213], v[34:37]
	s_setprio 0
	s_barrier
	v_lshl_add_u64 v[164:165], v[156:157], 0, s[16:17]
	s_add_i32 s38, s38, s27
	v_lshl_add_u64 v[166:167], v[164:165], 0, v[130:131]
	s_mov_b32 m0, s38
	v_lshl_add_u64 v[164:165], v[164:165], 0, v[144:145]
	global_load_lds_dwordx4 v[166:167], off
	s_add_i32 m0, s38, 0x2000
	s_nop 0
	global_load_lds_dwordx4 v[164:165], off
	s_waitcnt vmcnt(6)
	s_barrier
	s_setprio 1
	v_mfma_f32_16x16x32_bf16 v[30:33], v[214:217], v[180:183], v[30:33]
	v_mfma_f32_16x16x32_bf16 v[26:29], v[222:225], v[180:183], v[26:29]
	v_mfma_f32_16x16x32_bf16 v[22:25], v[214:217], v[188:191], v[22:25]
	v_mfma_f32_16x16x32_bf16 v[18:21], v[222:225], v[188:191], v[18:21]
	v_mfma_f32_16x16x32_bf16 v[14:17], v[214:217], v[196:199], v[14:17]
	v_mfma_f32_16x16x32_bf16 v[10:13], v[222:225], v[196:199], v[10:13]
	v_mfma_f32_16x16x32_bf16 v[6:9], v[214:217], v[204:207], v[6:9]
	v_mfma_f32_16x16x32_bf16 v[2:5], v[222:225], v[204:207], v[2:5]
	v_mfma_f32_16x16x32_bf16 v[30:33], v[218:221], v[184:187], v[30:33]
	v_mfma_f32_16x16x32_bf16 v[26:29], v[228:231], v[184:187], v[26:29]
	v_mfma_f32_16x16x32_bf16 v[22:25], v[218:221], v[192:195], v[22:25]
	v_mfma_f32_16x16x32_bf16 v[18:21], v[228:231], v[192:195], v[18:21]
	v_mfma_f32_16x16x32_bf16 v[14:17], v[218:221], v[200:203], v[14:17]
	v_mfma_f32_16x16x32_bf16 v[10:13], v[228:231], v[200:203], v[10:13]
	v_mfma_f32_16x16x32_bf16 v[6:9], v[218:221], v[210:213], v[6:9]
	v_mfma_f32_16x16x32_bf16 v[2:5], v[228:231], v[210:213], v[2:5]
	s_setprio 0
	s_add_i32 s38, 0, 0x18000
	v_add_u32_e32 v176, s38, v162
	s_barrier
	ds_read_b128 v[164:167], v176
	ds_read_b128 v[172:175], v176 offset:2048
	ds_read_b128 v[168:171], v176 offset:1024
	ds_read_b128 v[176:179], v176 offset:3072
	v_lshl_add_u64 v[214:215], v[232:233], 0, s[16:17]
	s_mov_b32 m0, s31
	v_lshl_add_u64 v[216:217], v[214:215], 0, v[130:131]
	ds_read_b128 v[180:183], v163 offset:32768
	ds_read_b128 v[188:191], v163 offset:34816
	ds_read_b128 v[196:199], v163 offset:36864
	ds_read_b128 v[204:207], v163 offset:38912
	ds_read_b128 v[184:187], v163 offset:33792
	ds_read_b128 v[192:195], v163 offset:35840
	ds_read_b128 v[200:203], v163 offset:37888
	ds_read_b128 v[210:213], v163 offset:39936
	global_load_lds_dwordx4 v[216:217], off
	v_lshl_add_u64 v[214:215], v[214:215], 0, v[144:145]
	s_mov_b32 m0, s34
	s_nop 0
	global_load_lds_dwordx4 v[214:215], off
	s_waitcnt lgkmcnt(8)
	s_barrier
	s_setprio 1
	s_waitcnt lgkmcnt(7)
	v_mfma_f32_16x16x32_bf16 v[126:129], v[164:167], v[180:183], v[126:129]
	v_mfma_f32_16x16x32_bf16 v[122:125], v[172:175], v[180:183], v[122:125]
	s_waitcnt lgkmcnt(6)
	v_mfma_f32_16x16x32_bf16 v[118:121], v[164:167], v[188:191], v[118:121]
	v_mfma_f32_16x16x32_bf16 v[114:117], v[172:175], v[188:191], v[114:117]
	s_waitcnt lgkmcnt(5)
	v_mfma_f32_16x16x32_bf16 v[110:113], v[164:167], v[196:199], v[110:113]
	v_mfma_f32_16x16x32_bf16 v[106:109], v[172:175], v[196:199], v[106:109]
	s_waitcnt lgkmcnt(4)
	v_mfma_f32_16x16x32_bf16 v[102:105], v[164:167], v[204:207], v[102:105]
	v_mfma_f32_16x16x32_bf16 v[98:101], v[172:175], v[204:207], v[98:101]
	s_waitcnt lgkmcnt(3)
	v_mfma_f32_16x16x32_bf16 v[126:129], v[168:171], v[184:187], v[126:129]
	v_mfma_f32_16x16x32_bf16 v[122:125], v[176:179], v[184:187], v[122:125]
	s_waitcnt lgkmcnt(2)
	v_mfma_f32_16x16x32_bf16 v[118:121], v[168:171], v[192:195], v[118:121]
	v_mfma_f32_16x16x32_bf16 v[114:117], v[176:179], v[192:195], v[114:117]
	s_waitcnt lgkmcnt(1)
	v_mfma_f32_16x16x32_bf16 v[110:113], v[168:171], v[200:203], v[110:113]
	v_mfma_f32_16x16x32_bf16 v[106:109], v[176:179], v[200:203], v[106:109]
	s_waitcnt lgkmcnt(0)
	v_mfma_f32_16x16x32_bf16 v[102:105], v[168:171], v[210:213], v[102:105]
	v_mfma_f32_16x16x32_bf16 v[98:101], v[176:179], v[210:213], v[98:101]
	s_setprio 0
	s_barrier
	s_add_i32 s39, 0, 0x1c000
	s_add_i32 s38, s38, s27
	v_add_u32_e32 v208, s39, v162
	v_lshl_add_u64 v[232:233], v[234:235], 0, s[18:19]
	s_mov_b32 m0, s38
	ds_read_b128 v[214:217], v208
	ds_read_b128 v[222:225], v208 offset:2048
	ds_read_b128 v[218:221], v208 offset:1024
	ds_read_b128 v[228:231], v208 offset:3072
	global_load_lds_dwordx4 v[232:233], off
	v_lshl_add_u64 v[232:233], v[236:237], 0, s[18:19]
	s_add_i32 m0, s38, 0x2000
	s_nop 0
	global_load_lds_dwordx4 v[232:233], off
	s_barrier
	s_setprio 1
	s_waitcnt lgkmcnt(3)
	v_mfma_f32_16x16x32_bf16 v[94:97], v[214:217], v[180:183], v[94:97]
	s_waitcnt lgkmcnt(2)
	v_mfma_f32_16x16x32_bf16 v[90:93], v[222:225], v[180:183], v[90:93]
	v_mfma_f32_16x16x32_bf16 v[86:89], v[214:217], v[188:191], v[86:89]
	v_mfma_f32_16x16x32_bf16 v[82:85], v[222:225], v[188:191], v[82:85]
	v_mfma_f32_16x16x32_bf16 v[78:81], v[214:217], v[196:199], v[78:81]
	v_mfma_f32_16x16x32_bf16 v[74:77], v[222:225], v[196:199], v[74:77]
	v_mfma_f32_16x16x32_bf16 v[70:73], v[214:217], v[204:207], v[70:73]
	v_mfma_f32_16x16x32_bf16 v[66:69], v[222:225], v[204:207], v[66:69]
	s_waitcnt lgkmcnt(1)
	v_mfma_f32_16x16x32_bf16 v[94:97], v[218:221], v[184:187], v[94:97]
	s_waitcnt lgkmcnt(0)
	v_mfma_f32_16x16x32_bf16 v[90:93], v[228:231], v[184:187], v[90:93]
	v_mfma_f32_16x16x32_bf16 v[86:89], v[218:221], v[192:195], v[86:89]
	v_mfma_f32_16x16x32_bf16 v[82:85], v[228:231], v[192:195], v[82:85]
	v_mfma_f32_16x16x32_bf16 v[78:81], v[218:221], v[200:203], v[78:81]
	v_mfma_f32_16x16x32_bf16 v[74:77], v[228:231], v[200:203], v[74:77]
	v_mfma_f32_16x16x32_bf16 v[70:73], v[218:221], v[210:213], v[70:73]
	v_mfma_f32_16x16x32_bf16 v[66:69], v[228:231], v[210:213], v[66:69]
	s_setprio 0
	s_mov_b32 m0, s35
	v_lshl_add_u64 v[232:233], v[238:239], 0, s[18:19]
	s_barrier
	ds_read_b128 v[180:183], v163 offset:49152
	ds_read_b128 v[188:191], v163 offset:51200
	ds_read_b128 v[196:199], v163 offset:53248
	ds_read_b128 v[204:207], v163 offset:55296
	ds_read_b128 v[184:187], v163 offset:50176
	ds_read_b128 v[192:195], v163 offset:52224
	ds_read_b128 v[200:203], v163 offset:54272
	ds_read_b128 v[210:213], v163 offset:56320
	global_load_lds_dwordx4 v[232:233], off
	v_lshl_add_u64 v[232:233], v[240:241], 0, s[18:19]
	s_mov_b32 m0, s36
	s_nop 0
	global_load_lds_dwordx4 v[232:233], off
	s_barrier
	s_setprio 1
	s_waitcnt lgkmcnt(7)
	v_mfma_f32_16x16x32_bf16 v[62:65], v[164:167], v[180:183], v[62:65]
	v_mfma_f32_16x16x32_bf16 v[58:61], v[172:175], v[180:183], v[58:61]
	s_waitcnt lgkmcnt(6)
	v_mfma_f32_16x16x32_bf16 v[54:57], v[164:167], v[188:191], v[54:57]
	v_mfma_f32_16x16x32_bf16 v[50:53], v[172:175], v[188:191], v[50:53]
	s_waitcnt lgkmcnt(5)
	v_mfma_f32_16x16x32_bf16 v[46:49], v[164:167], v[196:199], v[46:49]
	v_mfma_f32_16x16x32_bf16 v[42:45], v[172:175], v[196:199], v[42:45]
	s_waitcnt lgkmcnt(4)
	v_mfma_f32_16x16x32_bf16 v[38:41], v[164:167], v[204:207], v[38:41]
	v_mfma_f32_16x16x32_bf16 v[34:37], v[172:175], v[204:207], v[34:37]
	s_waitcnt lgkmcnt(3)
	v_mfma_f32_16x16x32_bf16 v[62:65], v[168:171], v[184:187], v[62:65]
	v_mfma_f32_16x16x32_bf16 v[58:61], v[176:179], v[184:187], v[58:61]
	s_waitcnt lgkmcnt(2)
	v_mfma_f32_16x16x32_bf16 v[54:57], v[168:171], v[192:195], v[54:57]
	v_mfma_f32_16x16x32_bf16 v[50:53], v[176:179], v[192:195], v[50:53]
	s_waitcnt lgkmcnt(1)
	v_mfma_f32_16x16x32_bf16 v[46:49], v[168:171], v[200:203], v[46:49]
	v_mfma_f32_16x16x32_bf16 v[42:45], v[176:179], v[200:203], v[42:45]
	s_waitcnt lgkmcnt(0)
	v_mfma_f32_16x16x32_bf16 v[38:41], v[168:171], v[210:213], v[38:41]
	v_mfma_f32_16x16x32_bf16 v[34:37], v[176:179], v[210:213], v[34:37]
	s_setprio 0
	s_barrier
	v_lshl_add_u64 v[156:157], v[156:157], 0, s[20:21]
	s_add_i32 s38, s39, s27
	v_lshl_add_u64 v[164:165], v[156:157], 0, v[130:131]
	s_mov_b32 m0, s38
	v_lshl_add_u64 v[156:157], v[156:157], 0, v[144:145]
	global_load_lds_dwordx4 v[164:165], off
	s_add_i32 m0, s38, 0x2000
	s_nop 0
	global_load_lds_dwordx4 v[156:157], off
	s_waitcnt vmcnt(6)
	s_barrier
	s_setprio 1
	v_mfma_f32_16x16x32_bf16 v[30:33], v[214:217], v[180:183], v[30:33]
	v_mfma_f32_16x16x32_bf16 v[26:29], v[222:225], v[180:183], v[26:29]
	v_mfma_f32_16x16x32_bf16 v[22:25], v[214:217], v[188:191], v[22:25]
	v_mfma_f32_16x16x32_bf16 v[18:21], v[222:225], v[188:191], v[18:21]
	v_mfma_f32_16x16x32_bf16 v[14:17], v[214:217], v[196:199], v[14:17]
	v_mfma_f32_16x16x32_bf16 v[10:13], v[222:225], v[196:199], v[10:13]
	v_mfma_f32_16x16x32_bf16 v[6:9], v[214:217], v[204:207], v[6:9]
	v_mfma_f32_16x16x32_bf16 v[2:5], v[222:225], v[204:207], v[2:5]
	v_mfma_f32_16x16x32_bf16 v[30:33], v[218:221], v[184:187], v[30:33]
	v_mfma_f32_16x16x32_bf16 v[26:29], v[228:231], v[184:187], v[26:29]
	v_mfma_f32_16x16x32_bf16 v[22:25], v[218:221], v[192:195], v[22:25]
	v_mfma_f32_16x16x32_bf16 v[18:21], v[228:231], v[192:195], v[18:21]
	v_mfma_f32_16x16x32_bf16 v[14:17], v[218:221], v[200:203], v[14:17]
	v_mfma_f32_16x16x32_bf16 v[10:13], v[228:231], v[200:203], v[10:13]
	v_mfma_f32_16x16x32_bf16 v[6:9], v[218:221], v[210:213], v[6:9]
	v_mfma_f32_16x16x32_bf16 v[2:5], v[228:231], v[210:213], v[2:5]
	s_setprio 0
	s_add_i32 s37, s37, 2
	s_add_u32 s4, s4, 0x100
	s_addc_u32 s5, s5, 0
	s_cmp_lt_u32 s37, 42
	s_barrier
	s_cbranch_scc1 .LBB0_1914
	s_waitcnt vmcnt(0)
	s_cmpk_gt_u32 s26, 0xff
	s_cbranch_scc1 .LBB0_1917
	s_barrier
